# adds hand-written INPROJ gates-branch epilogue and GLU with strict transcendental/plain VALU alternation
# speedup vs baseline: 1.0013x; 1.0013x over previous
; __device__ __forceinline__ void unpack8(const u32x4 w, f32x4& a, f32x4& b) { a = (f32x4){bflo(w.x), bfhi(w.x), bflo(w.y), bfhi(w.y)}; b = (f32x4){bflo(w.z), bfhi(w.z), bflo(w.w), bfhi(w.w)}; }
; __device__ __forceinline__ u32x4 pack8(const f32x4 a, const f32x4 b) { u32x4 w; w.x = cvt_pk_bf16(a[0], a[1]); w.y = cvt_pk_bf16(a[2], a[3]); w.z = cvt_pk_bf16(b[0], b[1]); w.w = cvt_pk_bf16(b[2], b[3]); return w; }
; __device__ __forceinline__ float sigmoidf_(float x) { return __builtin_amdgcn_rcpf(1.0f + __builtin_amdgcn_exp2f(-1.4426950408889634f * x)); }
; template <int MODE>
; __device__ __forceinline__ void epi_body(const Epi& E0, const f32x4 (&acc)[2][2][4][2], const Unit& u, int wr, int wc, int fr, int fq) {
;     ...
;                 } else if constexpr (MODE == EM_GLU) {
;                     const int c = u.pn * 256 + cl; const size_t off = (size_t)r * SSMW + c;
;                     f32x4 z0, z1; unpack8(*(const u32x4*)(E.z + off), z0, z1);
;                     const f32x4 b0 = *(const f32x4*)(E.bglu + c), b1 = *(const f32x4*)(E.bglu + c + 4);
; #pragma unroll
;                     for (int j = 0; j < 4; ++j) { v0[j] = z0[j] * sigmoidf_(v0[j] + b0[j]); v1[j] = z1[j] * sigmoidf_(v1[j] + b1[j]); }
;                     *(u32x4*)(E.yssm + off) = pack8(v0, v1);
.LBB0_236:
	s_cmp_lt_i32 s96, 2
	s_mov_b64 s[8:9], -1
	s_cbranch_scc1 .LBB0_242
	s_cmp_gt_i32 s96, 2
	s_cbranch_scc0 .LBB0_239
	v_mov_b32_e32 v0, v159
	s_mov_b64 s[8:9], 0
	v_readlane_b32 s22, v250, 21
	s_lshl_b32 s23, s21, 8
	s_add_i32 s22, s22, s23
	v_add_u32_e32 v130, s22, v159
	v_readlane_b32 s22, v250, 22
	s_lshl_b32 s23, s28, 8
	s_or_b32 s22, s22, s23
	v_lshl_add_u32 v131, v158, 3, s22
	v_readlane_b32 s26, v250, 3
	v_readlane_b32 s27, v250, 4
	s_add_u32 s34, s26, 0xee00000
	s_addc_u32 s35, s27, 0
	s_add_u32 s26, s26, 0x8e00000
	s_addc_u32 s27, s27, 0
	v_lshlrev_b32_e32 v132, 11, v130
	v_lshl_add_u32 v132, v131, 1, v132
	v_lshlrev_b32_e32 v133, 2, v131
	global_load_dwordx4 v[164:167], v133, s[78:79]
	global_load_dwordx4 v[168:171], v133, s[78:79] offset:16
	global_load_dwordx4 v[172:175], v133, s[78:79] offset:512
	global_load_dwordx4 v[176:179], v133, s[78:79] offset:528
	s_add_u32 s22, s26, 0x0
	s_addc_u32 s23, s27, 0
	global_load_dwordx4 v[184:187], v132, s[22:23] offset:0
	s_add_u32 s22, s26, 0x0
	s_addc_u32 s23, s27, 0
	global_load_dwordx4 v[188:191], v132, s[22:23] offset:256
	s_add_u32 s22, s26, 0x8000
	s_addc_u32 s23, s27, 0
	global_load_dwordx4 v[192:195], v132, s[22:23] offset:0
	s_add_u32 s22, s26, 0x8000
	s_addc_u32 s23, s27, 0
	global_load_dwordx4 v[216:219], v132, s[22:23] offset:256
	s_add_u32 s22, s26, 0x10000
	s_addc_u32 s23, s27, 0
	global_load_dwordx4 v[220:223], v132, s[22:23] offset:0
	s_add_u32 s22, s26, 0x10000
	s_addc_u32 s23, s27, 0
	global_load_dwordx4 v[224:227], v132, s[22:23] offset:256
	s_add_u32 s22, s26, 0x18000
	s_addc_u32 s23, s27, 0
	global_load_dwordx4 v[228:231], v132, s[22:23] offset:0
	s_add_u32 s22, s26, 0x18000
	s_addc_u32 s23, s27, 0
	global_load_dwordx4 v[232:235], v132, s[22:23] offset:256
	s_add_u32 s22, s26, 0x40000
	s_addc_u32 s23, s27, 0
	global_load_dwordx4 v[236:239], v132, s[22:23] offset:0
	s_add_u32 s22, s26, 0x40000
	s_addc_u32 s23, s27, 0
	global_load_dwordx4 v[240:243], v132, s[22:23] offset:256
	s_add_u32 s22, s26, 0x48000
	s_addc_u32 s23, s27, 0
	global_load_dwordx4 v[244:247], v132, s[22:23] offset:0
	s_waitcnt vmcnt(10)
	v_add_f32_e32 v126, v126, v164
	v_add_f32_e32 v127, v127, v165
	v_add_f32_e32 v128, v128, v166
	v_add_f32_e32 v129, v129, v167
	v_add_f32_e32 v122, v122, v168
	v_add_f32_e32 v123, v123, v169
	v_add_f32_e32 v124, v124, v170
	v_add_f32_e32 v125, v125, v171
	v_mul_f32_e32 v126, 0xbfb8aa3b, v126
	v_mul_f32_e32 v127, 0xbfb8aa3b, v127
	v_exp_f32_e32 v126, v126
	v_mul_f32_e32 v128, 0xbfb8aa3b, v128
	v_exp_f32_e32 v127, v127
	v_mul_f32_e32 v129, 0xbfb8aa3b, v129
	v_exp_f32_e32 v128, v128
	v_mul_f32_e32 v122, 0xbfb8aa3b, v122
	v_exp_f32_e32 v129, v129
	v_mul_f32_e32 v123, 0xbfb8aa3b, v123
	v_exp_f32_e32 v122, v122
	v_mul_f32_e32 v124, 0xbfb8aa3b, v124
	v_exp_f32_e32 v123, v123
	v_mul_f32_e32 v125, 0xbfb8aa3b, v125
	v_exp_f32_e32 v124, v124
	v_add_f32_e32 v126, 1.0, v126
	v_exp_f32_e32 v125, v125
	v_add_f32_e32 v127, 1.0, v127
	v_rcp_f32_e32 v126, v126
	v_add_f32_e32 v128, 1.0, v128
	v_rcp_f32_e32 v127, v127
	v_add_f32_e32 v129, 1.0, v129
	v_rcp_f32_e32 v128, v128
	v_add_f32_e32 v122, 1.0, v122
	v_rcp_f32_e32 v129, v129
	v_add_f32_e32 v123, 1.0, v123
	v_rcp_f32_e32 v122, v122
	v_add_f32_e32 v124, 1.0, v124
	v_rcp_f32_e32 v123, v123
	v_add_f32_e32 v125, 1.0, v125
	v_rcp_f32_e32 v124, v124
	v_lshlrev_b32_e32 v156, 16, v184
	v_rcp_f32_e32 v125, v125
	v_and_b32_e32 v157, 0xffff0000, v184
	v_lshlrev_b32_e32 v162, 16, v185
	v_and_b32_e32 v163, 0xffff0000, v185
	v_lshlrev_b32_e32 v182, 16, v186
	v_and_b32_e32 v183, 0xffff0000, v186
	v_lshlrev_b32_e32 v248, 16, v187
	v_and_b32_e32 v249, 0xffff0000, v187
	v_pk_mul_f32 v[126:127], v[126:127], v[156:157]
	v_pk_mul_f32 v[128:129], v[128:129], v[162:163]
	v_pk_mul_f32 v[122:123], v[122:123], v[182:183]
	v_pk_mul_f32 v[124:125], v[124:125], v[248:249]
	v_cvt_pk_bf16_f32 v148, v126, v127
	v_cvt_pk_bf16_f32 v149, v128, v129
	v_cvt_pk_bf16_f32 v150, v122, v123
	v_cvt_pk_bf16_f32 v151, v124, v125
	s_add_u32 s22, s34, 0x0
	s_addc_u32 s23, s35, 0
	global_store_dwordx4 v132, v[148:151], s[22:23] offset:0
	s_add_u32 s22, s26, 0x48000
	s_addc_u32 s23, s27, 0
	global_load_dwordx4 v[184:187], v132, s[22:23] offset:256
	s_waitcnt vmcnt(11)
	v_add_f32_e32 v118, v118, v172
	v_add_f32_e32 v119, v119, v173
	v_add_f32_e32 v120, v120, v174
	v_add_f32_e32 v121, v121, v175
	v_add_f32_e32 v114, v114, v176
	v_add_f32_e32 v115, v115, v177
	v_add_f32_e32 v116, v116, v178
	v_add_f32_e32 v117, v117, v179
	v_mul_f32_e32 v118, 0xbfb8aa3b, v118
	v_mul_f32_e32 v119, 0xbfb8aa3b, v119
	v_exp_f32_e32 v118, v118
	v_mul_f32_e32 v120, 0xbfb8aa3b, v120
	v_exp_f32_e32 v119, v119
	v_mul_f32_e32 v121, 0xbfb8aa3b, v121
	v_exp_f32_e32 v120, v120
	v_mul_f32_e32 v114, 0xbfb8aa3b, v114
	v_exp_f32_e32 v121, v121
	v_mul_f32_e32 v115, 0xbfb8aa3b, v115
	v_exp_f32_e32 v114, v114
	v_mul_f32_e32 v116, 0xbfb8aa3b, v116
	v_exp_f32_e32 v115, v115
	v_mul_f32_e32 v117, 0xbfb8aa3b, v117
	v_exp_f32_e32 v116, v116
	v_add_f32_e32 v118, 1.0, v118
	v_exp_f32_e32 v117, v117
	v_add_f32_e32 v119, 1.0, v119
	v_rcp_f32_e32 v118, v118
	v_add_f32_e32 v120, 1.0, v120
	v_rcp_f32_e32 v119, v119
	v_add_f32_e32 v121, 1.0, v121
	v_rcp_f32_e32 v120, v120
	v_add_f32_e32 v114, 1.0, v114
	v_rcp_f32_e32 v121, v121
	v_add_f32_e32 v115, 1.0, v115
	v_rcp_f32_e32 v114, v114
	v_add_f32_e32 v116, 1.0, v116
	v_rcp_f32_e32 v115, v115
	v_add_f32_e32 v117, 1.0, v117
	v_rcp_f32_e32 v116, v116
	v_lshlrev_b32_e32 v156, 16, v188
	v_rcp_f32_e32 v117, v117
	v_and_b32_e32 v157, 0xffff0000, v188
	v_lshlrev_b32_e32 v162, 16, v189
	v_and_b32_e32 v163, 0xffff0000, v189
	v_lshlrev_b32_e32 v182, 16, v190
	v_and_b32_e32 v183, 0xffff0000, v190
	v_lshlrev_b32_e32 v248, 16, v191
	v_and_b32_e32 v249, 0xffff0000, v191
	v_pk_mul_f32 v[118:119], v[118:119], v[156:157]
	v_pk_mul_f32 v[120:121], v[120:121], v[162:163]
	v_pk_mul_f32 v[114:115], v[114:115], v[182:183]
	v_pk_mul_f32 v[116:117], v[116:117], v[248:249]
	v_cvt_pk_bf16_f32 v152, v118, v119
	v_cvt_pk_bf16_f32 v153, v120, v121
	v_cvt_pk_bf16_f32 v154, v114, v115
	v_cvt_pk_bf16_f32 v155, v116, v117
	s_add_u32 s22, s34, 0x0
	s_addc_u32 s23, s35, 0
	global_store_dwordx4 v132, v[152:155], s[22:23] offset:256
	s_add_u32 s22, s26, 0x50000
	s_addc_u32 s23, s27, 0
	global_load_dwordx4 v[188:191], v132, s[22:23] offset:0
	s_waitcnt vmcnt(12)
; __device__ __forceinline__ void unpack8(const u32x4 w, f32x4& a, f32x4& b) { a = (f32x4){bflo(w.x), bfhi(w.x), bflo(w.y), bfhi(w.y)}; b = (f32x4){bflo(w.z), bfhi(w.z), bflo(w.w), bfhi(w.w)}; }
; __device__ __forceinline__ u32x4 pack8(const f32x4 a, const f32x4 b) { u32x4 w; w.x = cvt_pk_bf16(a[0], a[1]); w.y = cvt_pk_bf16(a[2], a[3]); w.z = cvt_pk_bf16(b[0], b[1]); w.w = cvt_pk_bf16(b[2], b[3]); return w; }
; __device__ __forceinline__ float sigmoidf_(float x) { return __builtin_amdgcn_rcpf(1.0f + __builtin_amdgcn_exp2f(-1.4426950408889634f * x)); }
; template <int MODE>
; __device__ __forceinline__ void epi_body(const Epi& E0, const f32x4 (&acc)[2][2][4][2], const Unit& u, int wr, int wc, int fr, int fq) {
;     ...
;                 } else if constexpr (MODE == EM_GLU) {
;                     const int c = u.pn * 256 + cl; const size_t off = (size_t)r * SSMW + c;
;                     f32x4 z0, z1; unpack8(*(const u32x4*)(E.z + off), z0, z1);
;                     const f32x4 b0 = *(const f32x4*)(E.bglu + c), b1 = *(const f32x4*)(E.bglu + c + 4);
; #pragma unroll
;                     for (int j = 0; j < 4; ++j) { v0[j] = z0[j] * sigmoidf_(v0[j] + b0[j]); v1[j] = z1[j] * sigmoidf_(v1[j] + b1[j]); }
;                     *(u32x4*)(E.yssm + off) = pack8(v0, v1);
	v_add_f32_e32 v110, v110, v164
	v_add_f32_e32 v111, v111, v165
	v_add_f32_e32 v112, v112, v166
	v_add_f32_e32 v113, v113, v167
	v_add_f32_e32 v106, v106, v168
	v_add_f32_e32 v107, v107, v169
	v_add_f32_e32 v108, v108, v170
	v_add_f32_e32 v109, v109, v171
	v_mul_f32_e32 v110, 0xbfb8aa3b, v110
	v_mul_f32_e32 v111, 0xbfb8aa3b, v111
	v_exp_f32_e32 v110, v110
	v_mul_f32_e32 v112, 0xbfb8aa3b, v112
	v_exp_f32_e32 v111, v111
	v_mul_f32_e32 v113, 0xbfb8aa3b, v113
	v_exp_f32_e32 v112, v112
	v_mul_f32_e32 v106, 0xbfb8aa3b, v106
	v_exp_f32_e32 v113, v113
	v_mul_f32_e32 v107, 0xbfb8aa3b, v107
	v_exp_f32_e32 v106, v106
	v_mul_f32_e32 v108, 0xbfb8aa3b, v108
	v_exp_f32_e32 v107, v107
	v_mul_f32_e32 v109, 0xbfb8aa3b, v109
	v_exp_f32_e32 v108, v108
	v_add_f32_e32 v110, 1.0, v110
	v_exp_f32_e32 v109, v109
	v_add_f32_e32 v111, 1.0, v111
	v_rcp_f32_e32 v110, v110
	v_add_f32_e32 v112, 1.0, v112
	v_rcp_f32_e32 v111, v111
	v_add_f32_e32 v113, 1.0, v113
	v_rcp_f32_e32 v112, v112
	v_add_f32_e32 v106, 1.0, v106
	v_rcp_f32_e32 v113, v113
	v_add_f32_e32 v107, 1.0, v107
	v_rcp_f32_e32 v106, v106
	v_add_f32_e32 v108, 1.0, v108
	v_rcp_f32_e32 v107, v107
	v_add_f32_e32 v109, 1.0, v109
	v_rcp_f32_e32 v108, v108
	v_lshlrev_b32_e32 v156, 16, v192
	v_rcp_f32_e32 v109, v109
	v_and_b32_e32 v157, 0xffff0000, v192
	v_lshlrev_b32_e32 v162, 16, v193
	v_and_b32_e32 v163, 0xffff0000, v193
	v_lshlrev_b32_e32 v182, 16, v194
	v_and_b32_e32 v183, 0xffff0000, v194
	v_lshlrev_b32_e32 v248, 16, v195
	v_and_b32_e32 v249, 0xffff0000, v195
	v_pk_mul_f32 v[110:111], v[110:111], v[156:157]
	v_pk_mul_f32 v[112:113], v[112:113], v[162:163]
	v_pk_mul_f32 v[106:107], v[106:107], v[182:183]
	v_pk_mul_f32 v[108:109], v[108:109], v[248:249]
	v_cvt_pk_bf16_f32 v148, v110, v111
	v_cvt_pk_bf16_f32 v149, v112, v113
	v_cvt_pk_bf16_f32 v150, v106, v107
	v_cvt_pk_bf16_f32 v151, v108, v109
	s_add_u32 s22, s34, 0x8000
	s_addc_u32 s23, s35, 0
	global_store_dwordx4 v132, v[148:151], s[22:23] offset:0
	s_add_u32 s22, s26, 0x50000
	s_addc_u32 s23, s27, 0
	global_load_dwordx4 v[192:195], v132, s[22:23] offset:256
	s_waitcnt vmcnt(13)
	v_add_f32_e32 v102, v102, v172
	v_add_f32_e32 v103, v103, v173
	v_add_f32_e32 v104, v104, v174
	v_add_f32_e32 v105, v105, v175
	v_add_f32_e32 v98, v98, v176
	v_add_f32_e32 v99, v99, v177
	v_add_f32_e32 v100, v100, v178
	v_add_f32_e32 v101, v101, v179
	v_mul_f32_e32 v102, 0xbfb8aa3b, v102
	v_mul_f32_e32 v103, 0xbfb8aa3b, v103
	v_exp_f32_e32 v102, v102
	v_mul_f32_e32 v104, 0xbfb8aa3b, v104
	v_exp_f32_e32 v103, v103
	v_mul_f32_e32 v105, 0xbfb8aa3b, v105
	v_exp_f32_e32 v104, v104
	v_mul_f32_e32 v98, 0xbfb8aa3b, v98
	v_exp_f32_e32 v105, v105
	v_mul_f32_e32 v99, 0xbfb8aa3b, v99
	v_exp_f32_e32 v98, v98
	v_mul_f32_e32 v100, 0xbfb8aa3b, v100
	v_exp_f32_e32 v99, v99
	v_mul_f32_e32 v101, 0xbfb8aa3b, v101
	v_exp_f32_e32 v100, v100
	v_add_f32_e32 v102, 1.0, v102
	v_exp_f32_e32 v101, v101
	v_add_f32_e32 v103, 1.0, v103
	v_rcp_f32_e32 v102, v102
	v_add_f32_e32 v104, 1.0, v104
	v_rcp_f32_e32 v103, v103
	v_add_f32_e32 v105, 1.0, v105
	v_rcp_f32_e32 v104, v104
	v_add_f32_e32 v98, 1.0, v98
	v_rcp_f32_e32 v105, v105
	v_add_f32_e32 v99, 1.0, v99
	v_rcp_f32_e32 v98, v98
	v_add_f32_e32 v100, 1.0, v100
	v_rcp_f32_e32 v99, v99
	v_add_f32_e32 v101, 1.0, v101
	v_rcp_f32_e32 v100, v100
	v_lshlrev_b32_e32 v156, 16, v216
	v_rcp_f32_e32 v101, v101
	v_and_b32_e32 v157, 0xffff0000, v216
	v_lshlrev_b32_e32 v162, 16, v217
	v_and_b32_e32 v163, 0xffff0000, v217
	v_lshlrev_b32_e32 v182, 16, v218
	v_and_b32_e32 v183, 0xffff0000, v218
	v_lshlrev_b32_e32 v248, 16, v219
	v_and_b32_e32 v249, 0xffff0000, v219
	v_pk_mul_f32 v[102:103], v[102:103], v[156:157]
	v_pk_mul_f32 v[104:105], v[104:105], v[162:163]
	v_pk_mul_f32 v[98:99], v[98:99], v[182:183]
	v_pk_mul_f32 v[100:101], v[100:101], v[248:249]
	v_cvt_pk_bf16_f32 v152, v102, v103
	v_cvt_pk_bf16_f32 v153, v104, v105
	v_cvt_pk_bf16_f32 v154, v98, v99
	v_cvt_pk_bf16_f32 v155, v100, v101
	s_add_u32 s22, s34, 0x8000
	s_addc_u32 s23, s35, 0
	global_store_dwordx4 v132, v[152:155], s[22:23] offset:256
	s_add_u32 s22, s26, 0x58000
	s_addc_u32 s23, s27, 0
	global_load_dwordx4 v[216:219], v132, s[22:23] offset:0
	s_waitcnt vmcnt(14)
	v_add_f32_e32 v94, v94, v164
	v_add_f32_e32 v95, v95, v165
	v_add_f32_e32 v96, v96, v166
	v_add_f32_e32 v97, v97, v167
	v_add_f32_e32 v90, v90, v168
	v_add_f32_e32 v91, v91, v169
	v_add_f32_e32 v92, v92, v170
	v_add_f32_e32 v93, v93, v171
	v_mul_f32_e32 v94, 0xbfb8aa3b, v94
	v_mul_f32_e32 v95, 0xbfb8aa3b, v95
	v_exp_f32_e32 v94, v94
	v_mul_f32_e32 v96, 0xbfb8aa3b, v96
	v_exp_f32_e32 v95, v95
	v_mul_f32_e32 v97, 0xbfb8aa3b, v97
	v_exp_f32_e32 v96, v96
	v_mul_f32_e32 v90, 0xbfb8aa3b, v90
	v_exp_f32_e32 v97, v97
	v_mul_f32_e32 v91, 0xbfb8aa3b, v91
	v_exp_f32_e32 v90, v90
	v_mul_f32_e32 v92, 0xbfb8aa3b, v92
	v_exp_f32_e32 v91, v91
	v_mul_f32_e32 v93, 0xbfb8aa3b, v93
	v_exp_f32_e32 v92, v92
	v_add_f32_e32 v94, 1.0, v94
	v_exp_f32_e32 v93, v93
	v_add_f32_e32 v95, 1.0, v95
	v_rcp_f32_e32 v94, v94
	v_add_f32_e32 v96, 1.0, v96
	v_rcp_f32_e32 v95, v95
	v_add_f32_e32 v97, 1.0, v97
	v_rcp_f32_e32 v96, v96
	v_add_f32_e32 v90, 1.0, v90
	v_rcp_f32_e32 v97, v97
	v_add_f32_e32 v91, 1.0, v91
	v_rcp_f32_e32 v90, v90
	v_add_f32_e32 v92, 1.0, v92
	v_rcp_f32_e32 v91, v91
	v_add_f32_e32 v93, 1.0, v93
	v_rcp_f32_e32 v92, v92
	v_lshlrev_b32_e32 v156, 16, v220
	v_rcp_f32_e32 v93, v93
	v_and_b32_e32 v157, 0xffff0000, v220
	v_lshlrev_b32_e32 v162, 16, v221
	v_and_b32_e32 v163, 0xffff0000, v221
	v_lshlrev_b32_e32 v182, 16, v222
	v_and_b32_e32 v183, 0xffff0000, v222
	v_lshlrev_b32_e32 v248, 16, v223
	v_and_b32_e32 v249, 0xffff0000, v223
	v_pk_mul_f32 v[94:95], v[94:95], v[156:157]
	v_pk_mul_f32 v[96:97], v[96:97], v[162:163]
	v_pk_mul_f32 v[90:91], v[90:91], v[182:183]
	v_pk_mul_f32 v[92:93], v[92:93], v[248:249]
	v_cvt_pk_bf16_f32 v148, v94, v95
	v_cvt_pk_bf16_f32 v149, v96, v97
	v_cvt_pk_bf16_f32 v150, v90, v91
	v_cvt_pk_bf16_f32 v151, v92, v93
	s_add_u32 s22, s34, 0x10000
	s_addc_u32 s23, s35, 0
	global_store_dwordx4 v132, v[148:151], s[22:23] offset:0
	s_add_u32 s22, s26, 0x58000
	s_addc_u32 s23, s27, 0
	global_load_dwordx4 v[220:223], v132, s[22:23] offset:256
	s_waitcnt vmcnt(15)
; __device__ __forceinline__ void unpack8(const u32x4 w, f32x4& a, f32x4& b) { a = (f32x4){bflo(w.x), bfhi(w.x), bflo(w.y), bfhi(w.y)}; b = (f32x4){bflo(w.z), bfhi(w.z), bflo(w.w), bfhi(w.w)}; }
; __device__ __forceinline__ u32x4 pack8(const f32x4 a, const f32x4 b) { u32x4 w; w.x = cvt_pk_bf16(a[0], a[1]); w.y = cvt_pk_bf16(a[2], a[3]); w.z = cvt_pk_bf16(b[0], b[1]); w.w = cvt_pk_bf16(b[2], b[3]); return w; }
; __device__ __forceinline__ float sigmoidf_(float x) { return __builtin_amdgcn_rcpf(1.0f + __builtin_amdgcn_exp2f(-1.4426950408889634f * x)); }
; template <int MODE>
; __device__ __forceinline__ void epi_body(const Epi& E0, const f32x4 (&acc)[2][2][4][2], const Unit& u, int wr, int wc, int fr, int fq) {
;     ...
;                 } else if constexpr (MODE == EM_GLU) {
;                     const int c = u.pn * 256 + cl; const size_t off = (size_t)r * SSMW + c;
;                     f32x4 z0, z1; unpack8(*(const u32x4*)(E.z + off), z0, z1);
;                     const f32x4 b0 = *(const f32x4*)(E.bglu + c), b1 = *(const f32x4*)(E.bglu + c + 4);
; #pragma unroll
;                     for (int j = 0; j < 4; ++j) { v0[j] = z0[j] * sigmoidf_(v0[j] + b0[j]); v1[j] = z1[j] * sigmoidf_(v1[j] + b1[j]); }
;                     *(u32x4*)(E.yssm + off) = pack8(v0, v1);
	v_add_f32_e32 v86, v86, v172
	v_add_f32_e32 v87, v87, v173
	v_add_f32_e32 v88, v88, v174
	v_add_f32_e32 v89, v89, v175
	v_add_f32_e32 v82, v82, v176
	v_add_f32_e32 v83, v83, v177
	v_add_f32_e32 v84, v84, v178
	v_add_f32_e32 v85, v85, v179
	v_mul_f32_e32 v86, 0xbfb8aa3b, v86
	v_mul_f32_e32 v87, 0xbfb8aa3b, v87
	v_exp_f32_e32 v86, v86
	v_mul_f32_e32 v88, 0xbfb8aa3b, v88
	v_exp_f32_e32 v87, v87
	v_mul_f32_e32 v89, 0xbfb8aa3b, v89
	v_exp_f32_e32 v88, v88
	v_mul_f32_e32 v82, 0xbfb8aa3b, v82
	v_exp_f32_e32 v89, v89
	v_mul_f32_e32 v83, 0xbfb8aa3b, v83
	v_exp_f32_e32 v82, v82
	v_mul_f32_e32 v84, 0xbfb8aa3b, v84
	v_exp_f32_e32 v83, v83
	v_mul_f32_e32 v85, 0xbfb8aa3b, v85
	v_exp_f32_e32 v84, v84
	v_add_f32_e32 v86, 1.0, v86
	v_exp_f32_e32 v85, v85
	v_add_f32_e32 v87, 1.0, v87
	v_rcp_f32_e32 v86, v86
	v_add_f32_e32 v88, 1.0, v88
	v_rcp_f32_e32 v87, v87
	v_add_f32_e32 v89, 1.0, v89
	v_rcp_f32_e32 v88, v88
	v_add_f32_e32 v82, 1.0, v82
	v_rcp_f32_e32 v89, v89
	v_add_f32_e32 v83, 1.0, v83
	v_rcp_f32_e32 v82, v82
	v_add_f32_e32 v84, 1.0, v84
	v_rcp_f32_e32 v83, v83
	v_add_f32_e32 v85, 1.0, v85
	v_rcp_f32_e32 v84, v84
	v_lshlrev_b32_e32 v156, 16, v224
	v_rcp_f32_e32 v85, v85
	v_and_b32_e32 v157, 0xffff0000, v224
	v_lshlrev_b32_e32 v162, 16, v225
	v_and_b32_e32 v163, 0xffff0000, v225
	v_lshlrev_b32_e32 v182, 16, v226
	v_and_b32_e32 v183, 0xffff0000, v226
	v_lshlrev_b32_e32 v248, 16, v227
	v_and_b32_e32 v249, 0xffff0000, v227
	v_pk_mul_f32 v[86:87], v[86:87], v[156:157]
	v_pk_mul_f32 v[88:89], v[88:89], v[162:163]
	v_pk_mul_f32 v[82:83], v[82:83], v[182:183]
	v_pk_mul_f32 v[84:85], v[84:85], v[248:249]
	v_cvt_pk_bf16_f32 v152, v86, v87
	v_cvt_pk_bf16_f32 v153, v88, v89
	v_cvt_pk_bf16_f32 v154, v82, v83
	v_cvt_pk_bf16_f32 v155, v84, v85
	s_add_u32 s22, s34, 0x10000
	s_addc_u32 s23, s35, 0
	global_store_dwordx4 v132, v[152:155], s[22:23] offset:256
	s_waitcnt vmcnt(15)
	v_add_f32_e32 v78, v78, v164
	v_add_f32_e32 v79, v79, v165
	v_add_f32_e32 v80, v80, v166
	v_add_f32_e32 v81, v81, v167
	v_add_f32_e32 v74, v74, v168
	v_add_f32_e32 v75, v75, v169
	v_add_f32_e32 v76, v76, v170
	v_add_f32_e32 v77, v77, v171
	v_mul_f32_e32 v78, 0xbfb8aa3b, v78
	v_mul_f32_e32 v79, 0xbfb8aa3b, v79
	v_exp_f32_e32 v78, v78
	v_mul_f32_e32 v80, 0xbfb8aa3b, v80
	v_exp_f32_e32 v79, v79
	v_mul_f32_e32 v81, 0xbfb8aa3b, v81
	v_exp_f32_e32 v80, v80
	v_mul_f32_e32 v74, 0xbfb8aa3b, v74
	v_exp_f32_e32 v81, v81
	v_mul_f32_e32 v75, 0xbfb8aa3b, v75
	v_exp_f32_e32 v74, v74
	v_mul_f32_e32 v76, 0xbfb8aa3b, v76
	v_exp_f32_e32 v75, v75
	v_mul_f32_e32 v77, 0xbfb8aa3b, v77
	v_exp_f32_e32 v76, v76
	v_add_f32_e32 v78, 1.0, v78
	v_exp_f32_e32 v77, v77
	v_add_f32_e32 v79, 1.0, v79
	v_rcp_f32_e32 v78, v78
	v_add_f32_e32 v80, 1.0, v80
	v_rcp_f32_e32 v79, v79
	v_add_f32_e32 v81, 1.0, v81
	v_rcp_f32_e32 v80, v80
	v_add_f32_e32 v74, 1.0, v74
	v_rcp_f32_e32 v81, v81
	v_add_f32_e32 v75, 1.0, v75
	v_rcp_f32_e32 v74, v74
	v_add_f32_e32 v76, 1.0, v76
	v_rcp_f32_e32 v75, v75
	v_add_f32_e32 v77, 1.0, v77
	v_rcp_f32_e32 v76, v76
	v_lshlrev_b32_e32 v156, 16, v228
	v_rcp_f32_e32 v77, v77
	v_and_b32_e32 v157, 0xffff0000, v228
	v_lshlrev_b32_e32 v162, 16, v229
	v_and_b32_e32 v163, 0xffff0000, v229
	v_lshlrev_b32_e32 v182, 16, v230
	v_and_b32_e32 v183, 0xffff0000, v230
	v_lshlrev_b32_e32 v248, 16, v231
	v_and_b32_e32 v249, 0xffff0000, v231
	v_pk_mul_f32 v[78:79], v[78:79], v[156:157]
	v_pk_mul_f32 v[80:81], v[80:81], v[162:163]
	v_pk_mul_f32 v[74:75], v[74:75], v[182:183]
	v_pk_mul_f32 v[76:77], v[76:77], v[248:249]
	v_cvt_pk_bf16_f32 v148, v78, v79
	v_cvt_pk_bf16_f32 v149, v80, v81
	v_cvt_pk_bf16_f32 v150, v74, v75
	v_cvt_pk_bf16_f32 v151, v76, v77
	s_add_u32 s22, s34, 0x18000
	s_addc_u32 s23, s35, 0
	global_store_dwordx4 v132, v[148:151], s[22:23] offset:0
	s_waitcnt vmcnt(15)
	v_add_f32_e32 v70, v70, v172
	v_add_f32_e32 v71, v71, v173
	v_add_f32_e32 v72, v72, v174
	v_add_f32_e32 v73, v73, v175
	v_add_f32_e32 v66, v66, v176
	v_add_f32_e32 v67, v67, v177
	v_add_f32_e32 v68, v68, v178
	v_add_f32_e32 v69, v69, v179
	v_mul_f32_e32 v70, 0xbfb8aa3b, v70
	v_mul_f32_e32 v71, 0xbfb8aa3b, v71
	v_exp_f32_e32 v70, v70
	v_mul_f32_e32 v72, 0xbfb8aa3b, v72
	v_exp_f32_e32 v71, v71
	v_mul_f32_e32 v73, 0xbfb8aa3b, v73
	v_exp_f32_e32 v72, v72
	v_mul_f32_e32 v66, 0xbfb8aa3b, v66
	v_exp_f32_e32 v73, v73
	v_mul_f32_e32 v67, 0xbfb8aa3b, v67
	v_exp_f32_e32 v66, v66
	v_mul_f32_e32 v68, 0xbfb8aa3b, v68
	v_exp_f32_e32 v67, v67
	v_mul_f32_e32 v69, 0xbfb8aa3b, v69
	v_exp_f32_e32 v68, v68
	v_add_f32_e32 v70, 1.0, v70
	v_exp_f32_e32 v69, v69
	v_add_f32_e32 v71, 1.0, v71
	v_rcp_f32_e32 v70, v70
	v_add_f32_e32 v72, 1.0, v72
	v_rcp_f32_e32 v71, v71
	v_add_f32_e32 v73, 1.0, v73
	v_rcp_f32_e32 v72, v72
	v_add_f32_e32 v66, 1.0, v66
	v_rcp_f32_e32 v73, v73
	v_add_f32_e32 v67, 1.0, v67
	v_rcp_f32_e32 v66, v66
	v_add_f32_e32 v68, 1.0, v68
	v_rcp_f32_e32 v67, v67
	v_add_f32_e32 v69, 1.0, v69
	v_rcp_f32_e32 v68, v68
	v_lshlrev_b32_e32 v156, 16, v232
	v_rcp_f32_e32 v69, v69
	v_and_b32_e32 v157, 0xffff0000, v232
	v_lshlrev_b32_e32 v162, 16, v233
	v_and_b32_e32 v163, 0xffff0000, v233
	v_lshlrev_b32_e32 v182, 16, v234
	v_and_b32_e32 v183, 0xffff0000, v234
	v_lshlrev_b32_e32 v248, 16, v235
	v_and_b32_e32 v249, 0xffff0000, v235
	v_pk_mul_f32 v[70:71], v[70:71], v[156:157]
	v_pk_mul_f32 v[72:73], v[72:73], v[162:163]
	v_pk_mul_f32 v[66:67], v[66:67], v[182:183]
	v_pk_mul_f32 v[68:69], v[68:69], v[248:249]
	v_cvt_pk_bf16_f32 v152, v70, v71
	v_cvt_pk_bf16_f32 v153, v72, v73
	v_cvt_pk_bf16_f32 v154, v66, v67
	v_cvt_pk_bf16_f32 v155, v68, v69
	s_add_u32 s22, s34, 0x18000
	s_addc_u32 s23, s35, 0
	global_store_dwordx4 v132, v[152:155], s[22:23] offset:256
	s_waitcnt vmcnt(15)
; __device__ __forceinline__ void unpack8(const u32x4 w, f32x4& a, f32x4& b) { a = (f32x4){bflo(w.x), bfhi(w.x), bflo(w.y), bfhi(w.y)}; b = (f32x4){bflo(w.z), bfhi(w.z), bflo(w.w), bfhi(w.w)}; }
; __device__ __forceinline__ u32x4 pack8(const f32x4 a, const f32x4 b) { u32x4 w; w.x = cvt_pk_bf16(a[0], a[1]); w.y = cvt_pk_bf16(a[2], a[3]); w.z = cvt_pk_bf16(b[0], b[1]); w.w = cvt_pk_bf16(b[2], b[3]); return w; }
; __device__ __forceinline__ float sigmoidf_(float x) { return __builtin_amdgcn_rcpf(1.0f + __builtin_amdgcn_exp2f(-1.4426950408889634f * x)); }
; template <int MODE>
; __device__ __forceinline__ void epi_body(const Epi& E0, const f32x4 (&acc)[2][2][4][2], const Unit& u, int wr, int wc, int fr, int fq) {
;     ...
;                 } else if constexpr (MODE == EM_GLU) {
;                     const int c = u.pn * 256 + cl; const size_t off = (size_t)r * SSMW + c;
;                     f32x4 z0, z1; unpack8(*(const u32x4*)(E.z + off), z0, z1);
;                     const f32x4 b0 = *(const f32x4*)(E.bglu + c), b1 = *(const f32x4*)(E.bglu + c + 4);
; #pragma unroll
;                     for (int j = 0; j < 4; ++j) { v0[j] = z0[j] * sigmoidf_(v0[j] + b0[j]); v1[j] = z1[j] * sigmoidf_(v1[j] + b1[j]); }
;                     *(u32x4*)(E.yssm + off) = pack8(v0, v1);
	v_add_f32_e32 v62, v62, v164
	v_add_f32_e32 v63, v63, v165
	v_add_f32_e32 v64, v64, v166
	v_add_f32_e32 v65, v65, v167
	v_add_f32_e32 v58, v58, v168
	v_add_f32_e32 v59, v59, v169
	v_add_f32_e32 v60, v60, v170
	v_add_f32_e32 v61, v61, v171
	v_mul_f32_e32 v62, 0xbfb8aa3b, v62
	v_mul_f32_e32 v63, 0xbfb8aa3b, v63
	v_exp_f32_e32 v62, v62
	v_mul_f32_e32 v64, 0xbfb8aa3b, v64
	v_exp_f32_e32 v63, v63
	v_mul_f32_e32 v65, 0xbfb8aa3b, v65
	v_exp_f32_e32 v64, v64
	v_mul_f32_e32 v58, 0xbfb8aa3b, v58
	v_exp_f32_e32 v65, v65
	v_mul_f32_e32 v59, 0xbfb8aa3b, v59
	v_exp_f32_e32 v58, v58
	v_mul_f32_e32 v60, 0xbfb8aa3b, v60
	v_exp_f32_e32 v59, v59
	v_mul_f32_e32 v61, 0xbfb8aa3b, v61
	v_exp_f32_e32 v60, v60
	v_add_f32_e32 v62, 1.0, v62
	v_exp_f32_e32 v61, v61
	v_add_f32_e32 v63, 1.0, v63
	v_rcp_f32_e32 v62, v62
	v_add_f32_e32 v64, 1.0, v64
	v_rcp_f32_e32 v63, v63
	v_add_f32_e32 v65, 1.0, v65
	v_rcp_f32_e32 v64, v64
	v_add_f32_e32 v58, 1.0, v58
	v_rcp_f32_e32 v65, v65
	v_add_f32_e32 v59, 1.0, v59
	v_rcp_f32_e32 v58, v58
	v_add_f32_e32 v60, 1.0, v60
	v_rcp_f32_e32 v59, v59
	v_add_f32_e32 v61, 1.0, v61
	v_rcp_f32_e32 v60, v60
	v_lshlrev_b32_e32 v156, 16, v236
	v_rcp_f32_e32 v61, v61
	v_and_b32_e32 v157, 0xffff0000, v236
	v_lshlrev_b32_e32 v162, 16, v237
	v_and_b32_e32 v163, 0xffff0000, v237
	v_lshlrev_b32_e32 v182, 16, v238
	v_and_b32_e32 v183, 0xffff0000, v238
	v_lshlrev_b32_e32 v248, 16, v239
	v_and_b32_e32 v249, 0xffff0000, v239
	v_pk_mul_f32 v[62:63], v[62:63], v[156:157]
	v_pk_mul_f32 v[64:65], v[64:65], v[162:163]
	v_pk_mul_f32 v[58:59], v[58:59], v[182:183]
	v_pk_mul_f32 v[60:61], v[60:61], v[248:249]
	v_cvt_pk_bf16_f32 v148, v62, v63
	v_cvt_pk_bf16_f32 v149, v64, v65
	v_cvt_pk_bf16_f32 v150, v58, v59
	v_cvt_pk_bf16_f32 v151, v60, v61
	s_add_u32 s22, s34, 0x40000
	s_addc_u32 s23, s35, 0
	global_store_dwordx4 v132, v[148:151], s[22:23] offset:0
	s_waitcnt vmcnt(15)
	v_add_f32_e32 v54, v54, v172
	v_add_f32_e32 v55, v55, v173
	v_add_f32_e32 v56, v56, v174
	v_add_f32_e32 v57, v57, v175
	v_add_f32_e32 v50, v50, v176
	v_add_f32_e32 v51, v51, v177
	v_add_f32_e32 v52, v52, v178
	v_add_f32_e32 v53, v53, v179
	v_mul_f32_e32 v54, 0xbfb8aa3b, v54
	v_mul_f32_e32 v55, 0xbfb8aa3b, v55
	v_exp_f32_e32 v54, v54
	v_mul_f32_e32 v56, 0xbfb8aa3b, v56
	v_exp_f32_e32 v55, v55
	v_mul_f32_e32 v57, 0xbfb8aa3b, v57
	v_exp_f32_e32 v56, v56
	v_mul_f32_e32 v50, 0xbfb8aa3b, v50
	v_exp_f32_e32 v57, v57
	v_mul_f32_e32 v51, 0xbfb8aa3b, v51
	v_exp_f32_e32 v50, v50
	v_mul_f32_e32 v52, 0xbfb8aa3b, v52
	v_exp_f32_e32 v51, v51
	v_mul_f32_e32 v53, 0xbfb8aa3b, v53
	v_exp_f32_e32 v52, v52
	v_add_f32_e32 v54, 1.0, v54
	v_exp_f32_e32 v53, v53
	v_add_f32_e32 v55, 1.0, v55
	v_rcp_f32_e32 v54, v54
	v_add_f32_e32 v56, 1.0, v56
	v_rcp_f32_e32 v55, v55
	v_add_f32_e32 v57, 1.0, v57
	v_rcp_f32_e32 v56, v56
	v_add_f32_e32 v50, 1.0, v50
	v_rcp_f32_e32 v57, v57
	v_add_f32_e32 v51, 1.0, v51
	v_rcp_f32_e32 v50, v50
	v_add_f32_e32 v52, 1.0, v52
	v_rcp_f32_e32 v51, v51
	v_add_f32_e32 v53, 1.0, v53
	v_rcp_f32_e32 v52, v52
	v_lshlrev_b32_e32 v156, 16, v240
	v_rcp_f32_e32 v53, v53
	v_and_b32_e32 v157, 0xffff0000, v240
	v_lshlrev_b32_e32 v162, 16, v241
	v_and_b32_e32 v163, 0xffff0000, v241
	v_lshlrev_b32_e32 v182, 16, v242
	v_and_b32_e32 v183, 0xffff0000, v242
	v_lshlrev_b32_e32 v248, 16, v243
	v_and_b32_e32 v249, 0xffff0000, v243
	v_pk_mul_f32 v[54:55], v[54:55], v[156:157]
	v_pk_mul_f32 v[56:57], v[56:57], v[162:163]
	v_pk_mul_f32 v[50:51], v[50:51], v[182:183]
	v_pk_mul_f32 v[52:53], v[52:53], v[248:249]
	v_cvt_pk_bf16_f32 v152, v54, v55
	v_cvt_pk_bf16_f32 v153, v56, v57
	v_cvt_pk_bf16_f32 v154, v50, v51
	v_cvt_pk_bf16_f32 v155, v52, v53
	s_add_u32 s22, s34, 0x40000
	s_addc_u32 s23, s35, 0
	global_store_dwordx4 v132, v[152:155], s[22:23] offset:256
	s_waitcnt vmcnt(15)
	v_add_f32_e32 v46, v46, v164
	v_add_f32_e32 v47, v47, v165
	v_add_f32_e32 v48, v48, v166
	v_add_f32_e32 v49, v49, v167
	v_add_f32_e32 v42, v42, v168
	v_add_f32_e32 v43, v43, v169
	v_add_f32_e32 v44, v44, v170
	v_add_f32_e32 v45, v45, v171
	v_mul_f32_e32 v46, 0xbfb8aa3b, v46
	v_mul_f32_e32 v47, 0xbfb8aa3b, v47
	v_exp_f32_e32 v46, v46
	v_mul_f32_e32 v48, 0xbfb8aa3b, v48
	v_exp_f32_e32 v47, v47
	v_mul_f32_e32 v49, 0xbfb8aa3b, v49
	v_exp_f32_e32 v48, v48
	v_mul_f32_e32 v42, 0xbfb8aa3b, v42
	v_exp_f32_e32 v49, v49
	v_mul_f32_e32 v43, 0xbfb8aa3b, v43
	v_exp_f32_e32 v42, v42
	v_mul_f32_e32 v44, 0xbfb8aa3b, v44
	v_exp_f32_e32 v43, v43
	v_mul_f32_e32 v45, 0xbfb8aa3b, v45
	v_exp_f32_e32 v44, v44
	v_add_f32_e32 v46, 1.0, v46
	v_exp_f32_e32 v45, v45
	v_add_f32_e32 v47, 1.0, v47
	v_rcp_f32_e32 v46, v46
	v_add_f32_e32 v48, 1.0, v48
	v_rcp_f32_e32 v47, v47
	v_add_f32_e32 v49, 1.0, v49
	v_rcp_f32_e32 v48, v48
	v_add_f32_e32 v42, 1.0, v42
	v_rcp_f32_e32 v49, v49
	v_add_f32_e32 v43, 1.0, v43
	v_rcp_f32_e32 v42, v42
	v_add_f32_e32 v44, 1.0, v44
	v_rcp_f32_e32 v43, v43
	v_add_f32_e32 v45, 1.0, v45
	v_rcp_f32_e32 v44, v44
	v_lshlrev_b32_e32 v156, 16, v244
	v_rcp_f32_e32 v45, v45
	v_and_b32_e32 v157, 0xffff0000, v244
	v_lshlrev_b32_e32 v162, 16, v245
	v_and_b32_e32 v163, 0xffff0000, v245
	v_lshlrev_b32_e32 v182, 16, v246
	v_and_b32_e32 v183, 0xffff0000, v246
	v_lshlrev_b32_e32 v248, 16, v247
	v_and_b32_e32 v249, 0xffff0000, v247
	v_pk_mul_f32 v[46:47], v[46:47], v[156:157]
	v_pk_mul_f32 v[48:49], v[48:49], v[162:163]
	v_pk_mul_f32 v[42:43], v[42:43], v[182:183]
	v_pk_mul_f32 v[44:45], v[44:45], v[248:249]
	v_cvt_pk_bf16_f32 v148, v46, v47
	v_cvt_pk_bf16_f32 v149, v48, v49
	v_cvt_pk_bf16_f32 v150, v42, v43
	v_cvt_pk_bf16_f32 v151, v44, v45
	s_add_u32 s22, s34, 0x48000
	s_addc_u32 s23, s35, 0
	global_store_dwordx4 v132, v[148:151], s[22:23] offset:0
	s_waitcnt vmcnt(14)
; __device__ __forceinline__ void unpack8(const u32x4 w, f32x4& a, f32x4& b) { a = (f32x4){bflo(w.x), bfhi(w.x), bflo(w.y), bfhi(w.y)}; b = (f32x4){bflo(w.z), bfhi(w.z), bflo(w.w), bfhi(w.w)}; }
; __device__ __forceinline__ u32x4 pack8(const f32x4 a, const f32x4 b) { u32x4 w; w.x = cvt_pk_bf16(a[0], a[1]); w.y = cvt_pk_bf16(a[2], a[3]); w.z = cvt_pk_bf16(b[0], b[1]); w.w = cvt_pk_bf16(b[2], b[3]); return w; }
; __device__ __forceinline__ float sigmoidf_(float x) { return __builtin_amdgcn_rcpf(1.0f + __builtin_amdgcn_exp2f(-1.4426950408889634f * x)); }
; template <int MODE>
; __device__ __forceinline__ void epi_body(const Epi& E0, const f32x4 (&acc)[2][2][4][2], const Unit& u, int wr, int wc, int fr, int fq) {
;     ...
;                 } else if constexpr (MODE == EM_GLU) {
;                     const int c = u.pn * 256 + cl; const size_t off = (size_t)r * SSMW + c;
;                     f32x4 z0, z1; unpack8(*(const u32x4*)(E.z + off), z0, z1);
;                     const f32x4 b0 = *(const f32x4*)(E.bglu + c), b1 = *(const f32x4*)(E.bglu + c + 4);
; #pragma unroll
;                     for (int j = 0; j < 4; ++j) { v0[j] = z0[j] * sigmoidf_(v0[j] + b0[j]); v1[j] = z1[j] * sigmoidf_(v1[j] + b1[j]); }
;                     *(u32x4*)(E.yssm + off) = pack8(v0, v1);
	v_add_f32_e32 v38, v38, v172
	v_add_f32_e32 v39, v39, v173
	v_add_f32_e32 v40, v40, v174
	v_add_f32_e32 v41, v41, v175
	v_add_f32_e32 v34, v34, v176
	v_add_f32_e32 v35, v35, v177
	v_add_f32_e32 v36, v36, v178
	v_add_f32_e32 v37, v37, v179
	v_mul_f32_e32 v38, 0xbfb8aa3b, v38
	v_mul_f32_e32 v39, 0xbfb8aa3b, v39
	v_exp_f32_e32 v38, v38
	v_mul_f32_e32 v40, 0xbfb8aa3b, v40
	v_exp_f32_e32 v39, v39
	v_mul_f32_e32 v41, 0xbfb8aa3b, v41
	v_exp_f32_e32 v40, v40
	v_mul_f32_e32 v34, 0xbfb8aa3b, v34
	v_exp_f32_e32 v41, v41
	v_mul_f32_e32 v35, 0xbfb8aa3b, v35
	v_exp_f32_e32 v34, v34
	v_mul_f32_e32 v36, 0xbfb8aa3b, v36
	v_exp_f32_e32 v35, v35
	v_mul_f32_e32 v37, 0xbfb8aa3b, v37
	v_exp_f32_e32 v36, v36
	v_add_f32_e32 v38, 1.0, v38
	v_exp_f32_e32 v37, v37
	v_add_f32_e32 v39, 1.0, v39
	v_rcp_f32_e32 v38, v38
	v_add_f32_e32 v40, 1.0, v40
	v_rcp_f32_e32 v39, v39
	v_add_f32_e32 v41, 1.0, v41
	v_rcp_f32_e32 v40, v40
	v_add_f32_e32 v34, 1.0, v34
	v_rcp_f32_e32 v41, v41
	v_add_f32_e32 v35, 1.0, v35
	v_rcp_f32_e32 v34, v34
	v_add_f32_e32 v36, 1.0, v36
	v_rcp_f32_e32 v35, v35
	v_add_f32_e32 v37, 1.0, v37
	v_rcp_f32_e32 v36, v36
	v_lshlrev_b32_e32 v156, 16, v184
	v_rcp_f32_e32 v37, v37
	v_and_b32_e32 v157, 0xffff0000, v184
	v_lshlrev_b32_e32 v162, 16, v185
	v_and_b32_e32 v163, 0xffff0000, v185
	v_lshlrev_b32_e32 v182, 16, v186
	v_and_b32_e32 v183, 0xffff0000, v186
	v_lshlrev_b32_e32 v248, 16, v187
	v_and_b32_e32 v249, 0xffff0000, v187
	v_pk_mul_f32 v[38:39], v[38:39], v[156:157]
	v_pk_mul_f32 v[40:41], v[40:41], v[162:163]
	v_pk_mul_f32 v[34:35], v[34:35], v[182:183]
	v_pk_mul_f32 v[36:37], v[36:37], v[248:249]
	v_cvt_pk_bf16_f32 v152, v38, v39
	v_cvt_pk_bf16_f32 v153, v40, v41
	v_cvt_pk_bf16_f32 v154, v34, v35
	v_cvt_pk_bf16_f32 v155, v36, v37
	s_add_u32 s22, s34, 0x48000
	s_addc_u32 s23, s35, 0
	global_store_dwordx4 v132, v[152:155], s[22:23] offset:256
	s_waitcnt vmcnt(13)
	v_add_f32_e32 v30, v30, v164
	v_add_f32_e32 v31, v31, v165
	v_add_f32_e32 v32, v32, v166
	v_add_f32_e32 v33, v33, v167
	v_add_f32_e32 v26, v26, v168
	v_add_f32_e32 v27, v27, v169
	v_add_f32_e32 v28, v28, v170
	v_add_f32_e32 v29, v29, v171
	v_mul_f32_e32 v30, 0xbfb8aa3b, v30
	v_mul_f32_e32 v31, 0xbfb8aa3b, v31
	v_exp_f32_e32 v30, v30
	v_mul_f32_e32 v32, 0xbfb8aa3b, v32
	v_exp_f32_e32 v31, v31
	v_mul_f32_e32 v33, 0xbfb8aa3b, v33
	v_exp_f32_e32 v32, v32
	v_mul_f32_e32 v26, 0xbfb8aa3b, v26
	v_exp_f32_e32 v33, v33
	v_mul_f32_e32 v27, 0xbfb8aa3b, v27
	v_exp_f32_e32 v26, v26
	v_mul_f32_e32 v28, 0xbfb8aa3b, v28
	v_exp_f32_e32 v27, v27
	v_mul_f32_e32 v29, 0xbfb8aa3b, v29
	v_exp_f32_e32 v28, v28
	v_add_f32_e32 v30, 1.0, v30
	v_exp_f32_e32 v29, v29
	v_add_f32_e32 v31, 1.0, v31
	v_rcp_f32_e32 v30, v30
	v_add_f32_e32 v32, 1.0, v32
	v_rcp_f32_e32 v31, v31
	v_add_f32_e32 v33, 1.0, v33
	v_rcp_f32_e32 v32, v32
	v_add_f32_e32 v26, 1.0, v26
	v_rcp_f32_e32 v33, v33
	v_add_f32_e32 v27, 1.0, v27
	v_rcp_f32_e32 v26, v26
	v_add_f32_e32 v28, 1.0, v28
	v_rcp_f32_e32 v27, v27
	v_add_f32_e32 v29, 1.0, v29
	v_rcp_f32_e32 v28, v28
	v_lshlrev_b32_e32 v156, 16, v188
	v_rcp_f32_e32 v29, v29
	v_and_b32_e32 v157, 0xffff0000, v188
	v_lshlrev_b32_e32 v162, 16, v189
	v_and_b32_e32 v163, 0xffff0000, v189
	v_lshlrev_b32_e32 v182, 16, v190
	v_and_b32_e32 v183, 0xffff0000, v190
	v_lshlrev_b32_e32 v248, 16, v191
	v_and_b32_e32 v249, 0xffff0000, v191
	v_pk_mul_f32 v[30:31], v[30:31], v[156:157]
	v_pk_mul_f32 v[32:33], v[32:33], v[162:163]
	v_pk_mul_f32 v[26:27], v[26:27], v[182:183]
	v_pk_mul_f32 v[28:29], v[28:29], v[248:249]
	v_cvt_pk_bf16_f32 v148, v30, v31
	v_cvt_pk_bf16_f32 v149, v32, v33
	v_cvt_pk_bf16_f32 v150, v26, v27
	v_cvt_pk_bf16_f32 v151, v28, v29
	s_add_u32 s22, s34, 0x50000
	s_addc_u32 s23, s35, 0
	global_store_dwordx4 v132, v[148:151], s[22:23] offset:0
	s_waitcnt vmcnt(12)
; __device__ __forceinline__ void unpack8(const u32x4 w, f32x4& a, f32x4& b) { a = (f32x4){bflo(w.x), bfhi(w.x), bflo(w.y), bfhi(w.y)}; b = (f32x4){bflo(w.z), bfhi(w.z), bflo(w.w), bfhi(w.w)}; }
; __device__ __forceinline__ u32x4 pack8(const f32x4 a, const f32x4 b) { u32x4 w; w.x = cvt_pk_bf16(a[0], a[1]); w.y = cvt_pk_bf16(a[2], a[3]); w.z = cvt_pk_bf16(b[0], b[1]); w.w = cvt_pk_bf16(b[2], b[3]); return w; }
; __device__ __forceinline__ float sigmoidf_(float x) { return __builtin_amdgcn_rcpf(1.0f + __builtin_amdgcn_exp2f(-1.4426950408889634f * x)); }
; template <int MODE>
; __device__ __forceinline__ void epi_body(const Epi& E0, const f32x4 (&acc)[2][2][4][2], const Unit& u, int wr, int wc, int fr, int fq) {
;     ...
;                 } else if constexpr (MODE == EM_GLU) {
;                     const int c = u.pn * 256 + cl; const size_t off = (size_t)r * SSMW + c;
;                     f32x4 z0, z1; unpack8(*(const u32x4*)(E.z + off), z0, z1);
;                     const f32x4 b0 = *(const f32x4*)(E.bglu + c), b1 = *(const f32x4*)(E.bglu + c + 4);
; #pragma unroll
;                     for (int j = 0; j < 4; ++j) { v0[j] = z0[j] * sigmoidf_(v0[j] + b0[j]); v1[j] = z1[j] * sigmoidf_(v1[j] + b1[j]); }
;                     *(u32x4*)(E.yssm + off) = pack8(v0, v1);
	v_add_f32_e32 v22, v22, v172
	v_add_f32_e32 v23, v23, v173
	v_add_f32_e32 v24, v24, v174
	v_add_f32_e32 v25, v25, v175
	v_add_f32_e32 v18, v18, v176
	v_add_f32_e32 v19, v19, v177
	v_add_f32_e32 v20, v20, v178
	v_add_f32_e32 v21, v21, v179
	v_mul_f32_e32 v22, 0xbfb8aa3b, v22
	v_mul_f32_e32 v23, 0xbfb8aa3b, v23
	v_exp_f32_e32 v22, v22
	v_mul_f32_e32 v24, 0xbfb8aa3b, v24
	v_exp_f32_e32 v23, v23
	v_mul_f32_e32 v25, 0xbfb8aa3b, v25
	v_exp_f32_e32 v24, v24
	v_mul_f32_e32 v18, 0xbfb8aa3b, v18
	v_exp_f32_e32 v25, v25
	v_mul_f32_e32 v19, 0xbfb8aa3b, v19
	v_exp_f32_e32 v18, v18
	v_mul_f32_e32 v20, 0xbfb8aa3b, v20
	v_exp_f32_e32 v19, v19
	v_mul_f32_e32 v21, 0xbfb8aa3b, v21
	v_exp_f32_e32 v20, v20
	v_add_f32_e32 v22, 1.0, v22
	v_exp_f32_e32 v21, v21
	v_add_f32_e32 v23, 1.0, v23
	v_rcp_f32_e32 v22, v22
	v_add_f32_e32 v24, 1.0, v24
	v_rcp_f32_e32 v23, v23
	v_add_f32_e32 v25, 1.0, v25
	v_rcp_f32_e32 v24, v24
	v_add_f32_e32 v18, 1.0, v18
	v_rcp_f32_e32 v25, v25
	v_add_f32_e32 v19, 1.0, v19
	v_rcp_f32_e32 v18, v18
	v_add_f32_e32 v20, 1.0, v20
	v_rcp_f32_e32 v19, v19
	v_add_f32_e32 v21, 1.0, v21
	v_rcp_f32_e32 v20, v20
	v_lshlrev_b32_e32 v156, 16, v192
	v_rcp_f32_e32 v21, v21
	v_and_b32_e32 v157, 0xffff0000, v192
	v_lshlrev_b32_e32 v162, 16, v193
	v_and_b32_e32 v163, 0xffff0000, v193
	v_lshlrev_b32_e32 v182, 16, v194
	v_and_b32_e32 v183, 0xffff0000, v194
	v_lshlrev_b32_e32 v248, 16, v195
	v_and_b32_e32 v249, 0xffff0000, v195
	v_pk_mul_f32 v[22:23], v[22:23], v[156:157]
	v_pk_mul_f32 v[24:25], v[24:25], v[162:163]
	v_pk_mul_f32 v[18:19], v[18:19], v[182:183]
	v_pk_mul_f32 v[20:21], v[20:21], v[248:249]
	v_cvt_pk_bf16_f32 v152, v22, v23
	v_cvt_pk_bf16_f32 v153, v24, v25
	v_cvt_pk_bf16_f32 v154, v18, v19
	v_cvt_pk_bf16_f32 v155, v20, v21
	s_add_u32 s22, s34, 0x50000
	s_addc_u32 s23, s35, 0
	global_store_dwordx4 v132, v[152:155], s[22:23] offset:256
	s_waitcnt vmcnt(11)
	v_add_f32_e32 v14, v14, v164
	v_add_f32_e32 v15, v15, v165
	v_add_f32_e32 v16, v16, v166
	v_add_f32_e32 v17, v17, v167
	v_add_f32_e32 v10, v10, v168
	v_add_f32_e32 v11, v11, v169
	v_add_f32_e32 v12, v12, v170
	v_add_f32_e32 v13, v13, v171
	v_mul_f32_e32 v14, 0xbfb8aa3b, v14
	v_mul_f32_e32 v15, 0xbfb8aa3b, v15
	v_exp_f32_e32 v14, v14
	v_mul_f32_e32 v16, 0xbfb8aa3b, v16
	v_exp_f32_e32 v15, v15
	v_mul_f32_e32 v17, 0xbfb8aa3b, v17
	v_exp_f32_e32 v16, v16
	v_mul_f32_e32 v10, 0xbfb8aa3b, v10
	v_exp_f32_e32 v17, v17
	v_mul_f32_e32 v11, 0xbfb8aa3b, v11
	v_exp_f32_e32 v10, v10
	v_mul_f32_e32 v12, 0xbfb8aa3b, v12
	v_exp_f32_e32 v11, v11
	v_mul_f32_e32 v13, 0xbfb8aa3b, v13
	v_exp_f32_e32 v12, v12
	v_add_f32_e32 v14, 1.0, v14
	v_exp_f32_e32 v13, v13
	v_add_f32_e32 v15, 1.0, v15
	v_rcp_f32_e32 v14, v14
	v_add_f32_e32 v16, 1.0, v16
	v_rcp_f32_e32 v15, v15
	v_add_f32_e32 v17, 1.0, v17
	v_rcp_f32_e32 v16, v16
	v_add_f32_e32 v10, 1.0, v10
	v_rcp_f32_e32 v17, v17
	v_add_f32_e32 v11, 1.0, v11
	v_rcp_f32_e32 v10, v10
	v_add_f32_e32 v12, 1.0, v12
	v_rcp_f32_e32 v11, v11
	v_add_f32_e32 v13, 1.0, v13
	v_rcp_f32_e32 v12, v12
	v_lshlrev_b32_e32 v156, 16, v216
	v_rcp_f32_e32 v13, v13
	v_and_b32_e32 v157, 0xffff0000, v216
	v_lshlrev_b32_e32 v162, 16, v217
	v_and_b32_e32 v163, 0xffff0000, v217
	v_lshlrev_b32_e32 v182, 16, v218
	v_and_b32_e32 v183, 0xffff0000, v218
	v_lshlrev_b32_e32 v248, 16, v219
	v_and_b32_e32 v249, 0xffff0000, v219
	v_pk_mul_f32 v[14:15], v[14:15], v[156:157]
	v_pk_mul_f32 v[16:17], v[16:17], v[162:163]
	v_pk_mul_f32 v[10:11], v[10:11], v[182:183]
	v_pk_mul_f32 v[12:13], v[12:13], v[248:249]
	v_cvt_pk_bf16_f32 v148, v14, v15
	v_cvt_pk_bf16_f32 v149, v16, v17
	v_cvt_pk_bf16_f32 v150, v10, v11
	v_cvt_pk_bf16_f32 v151, v12, v13
	s_add_u32 s22, s34, 0x58000
	s_addc_u32 s23, s35, 0
	global_store_dwordx4 v132, v[148:151], s[22:23] offset:0
	s_waitcnt vmcnt(10)
	v_add_f32_e32 v6, v6, v172
	v_add_f32_e32 v7, v7, v173
	v_add_f32_e32 v8, v8, v174
	v_add_f32_e32 v9, v9, v175
	v_add_f32_e32 v2, v2, v176
	v_add_f32_e32 v3, v3, v177
	v_add_f32_e32 v4, v4, v178
	v_add_f32_e32 v5, v5, v179
	v_mul_f32_e32 v6, 0xbfb8aa3b, v6
	v_mul_f32_e32 v7, 0xbfb8aa3b, v7
	v_exp_f32_e32 v6, v6
	v_mul_f32_e32 v8, 0xbfb8aa3b, v8
	v_exp_f32_e32 v7, v7
	v_mul_f32_e32 v9, 0xbfb8aa3b, v9
	v_exp_f32_e32 v8, v8
	v_mul_f32_e32 v2, 0xbfb8aa3b, v2
	v_exp_f32_e32 v9, v9
	v_mul_f32_e32 v3, 0xbfb8aa3b, v3
	v_exp_f32_e32 v2, v2
	v_mul_f32_e32 v4, 0xbfb8aa3b, v4
	v_exp_f32_e32 v3, v3
	v_mul_f32_e32 v5, 0xbfb8aa3b, v5
	v_exp_f32_e32 v4, v4
	v_add_f32_e32 v6, 1.0, v6
	v_exp_f32_e32 v5, v5
	v_add_f32_e32 v7, 1.0, v7
	v_rcp_f32_e32 v6, v6
	v_add_f32_e32 v8, 1.0, v8
	v_rcp_f32_e32 v7, v7
	v_add_f32_e32 v9, 1.0, v9
	v_rcp_f32_e32 v8, v8
	v_add_f32_e32 v2, 1.0, v2
	v_rcp_f32_e32 v9, v9
	v_add_f32_e32 v3, 1.0, v3
	v_rcp_f32_e32 v2, v2
	v_add_f32_e32 v4, 1.0, v4
	v_rcp_f32_e32 v3, v3
	v_add_f32_e32 v5, 1.0, v5
	v_rcp_f32_e32 v4, v4
	v_lshlrev_b32_e32 v156, 16, v220
	v_rcp_f32_e32 v5, v5
	v_and_b32_e32 v157, 0xffff0000, v220
	v_lshlrev_b32_e32 v162, 16, v221
	v_and_b32_e32 v163, 0xffff0000, v221
	v_lshlrev_b32_e32 v182, 16, v222
	v_and_b32_e32 v183, 0xffff0000, v222
	v_lshlrev_b32_e32 v248, 16, v223
	v_and_b32_e32 v249, 0xffff0000, v223
	v_pk_mul_f32 v[6:7], v[6:7], v[156:157]
	v_pk_mul_f32 v[8:9], v[8:9], v[162:163]
	v_pk_mul_f32 v[2:3], v[2:3], v[182:183]
	v_pk_mul_f32 v[4:5], v[4:5], v[248:249]
	v_cvt_pk_bf16_f32 v152, v6, v7
	v_cvt_pk_bf16_f32 v153, v8, v9
	v_cvt_pk_bf16_f32 v154, v2, v3
	v_cvt_pk_bf16_f32 v155, v4, v5
	s_add_u32 s22, s34, 0x58000
	s_addc_u32 s23, s35, 0
	global_store_dwordx4 v132, v[152:155], s[22:23] offset:256
	s_mov_b64 s[8:9], 0

; __device__ __forceinline__ u32x4 pack8(const f32x4 a, const f32x4 b) { u32x4 w; w.x = cvt_pk_bf16(a[0], a[1]); w.y = cvt_pk_bf16(a[2], a[3]); w.z = cvt_pk_bf16(b[0], b[1]); w.w = cvt_pk_bf16(b[2], b[3]); return w; }
; __device__ __forceinline__ float sigmoidf_(float x) { return __builtin_amdgcn_rcpf(1.0f + __builtin_amdgcn_exp2f(-1.4426950408889634f * x)); }
; template <int MODE>
; __device__ __forceinline__ void epi_body(const Epi& E0, const f32x4 (&acc)[2][2][4][2], const Unit& u, int wr, int wc, int fr, int fq) {
;     ...
;                     } else {
; #pragma unroll
;                         for (int j = 0; j < 4; ++j) { v0[j] = sigmoidf_(v0[j]); v1[j] = sigmoidf_(v1[j]); }
;                         *(u32x4*)(E.gates + (size_t)r * GATEW + (u.pn - 22) * 256 + cl) = pack8(v0, v1);
;                     }
.LBB0_245:
	s_andn2_b64 vcc, exec, s[8:9]
	s_cbranch_vccnz .LBB0_374
	s_cmp_lt_i32 s28, 22
	s_cbranch_scc1 .Lepi_inproj_orig
	v_readlane_b32 s22, v250, 21
	s_lshl_b32 s23, s21, 8
	s_add_i32 s22, s22, s23
	v_add_u32_e32 v130, s22, v159
	v_readlane_b32 s22, v250, 22
	s_lshl_b32 s23, s28, 8
	s_or_b32 s22, s22, s23
	v_lshl_add_u32 v131, v158, 3, s22
	v_readlane_b32 s34, v251, 63
	v_readlane_b32 s35, v250, 0
	s_add_u32 s34, s34, 0x27000000
	s_addc_u32 s35, s35, 0
	v_lshlrev_b32_e32 v132, 13, v130
	v_lshl_add_u32 v132, v131, 1, v132
	v_add_u32_e32 v132, 0xffffd400, v132
	v_mul_f32_e32 v126, 0xbfb8aa3b, v126
	v_mul_f32_e32 v127, 0xbfb8aa3b, v127
	v_exp_f32_e32 v126, v126
	v_mul_f32_e32 v128, 0xbfb8aa3b, v128
	v_exp_f32_e32 v127, v127
	v_mul_f32_e32 v129, 0xbfb8aa3b, v129
	v_exp_f32_e32 v128, v128
	v_mul_f32_e32 v122, 0xbfb8aa3b, v122
	v_exp_f32_e32 v129, v129
	v_mul_f32_e32 v123, 0xbfb8aa3b, v123
	v_exp_f32_e32 v122, v122
	v_mul_f32_e32 v124, 0xbfb8aa3b, v124
	v_exp_f32_e32 v123, v123
	v_mul_f32_e32 v125, 0xbfb8aa3b, v125
	v_exp_f32_e32 v124, v124
	v_add_f32_e32 v126, 1.0, v126
	v_exp_f32_e32 v125, v125
	v_add_f32_e32 v127, 1.0, v127
	v_rcp_f32_e32 v126, v126
	v_add_f32_e32 v128, 1.0, v128
	v_rcp_f32_e32 v127, v127
	v_add_f32_e32 v129, 1.0, v129
	v_rcp_f32_e32 v128, v128
	v_add_f32_e32 v122, 1.0, v122
	v_rcp_f32_e32 v129, v129
	v_add_f32_e32 v123, 1.0, v123
	v_rcp_f32_e32 v122, v122
	v_add_f32_e32 v124, 1.0, v124
	v_rcp_f32_e32 v123, v123
	v_add_f32_e32 v125, 1.0, v125
	v_rcp_f32_e32 v124, v124
	v_rcp_f32_e32 v125, v125
	s_add_u32 s22, s34, 0x0
	s_addc_u32 s23, s35, 0
	v_cvt_pk_bf16_f32 v148, v126, v127
	v_cvt_pk_bf16_f32 v149, v128, v129
	v_cvt_pk_bf16_f32 v150, v122, v123
	v_cvt_pk_bf16_f32 v151, v124, v125
	global_store_dwordx4 v132, v[148:151], s[22:23] offset:0
	v_mul_f32_e32 v118, 0xbfb8aa3b, v118
	v_mul_f32_e32 v119, 0xbfb8aa3b, v119
	v_exp_f32_e32 v118, v118
	v_mul_f32_e32 v120, 0xbfb8aa3b, v120
	v_exp_f32_e32 v119, v119
	v_mul_f32_e32 v121, 0xbfb8aa3b, v121
	v_exp_f32_e32 v120, v120
	v_mul_f32_e32 v114, 0xbfb8aa3b, v114
	v_exp_f32_e32 v121, v121
	v_mul_f32_e32 v115, 0xbfb8aa3b, v115
	v_exp_f32_e32 v114, v114
	v_mul_f32_e32 v116, 0xbfb8aa3b, v116
	v_exp_f32_e32 v115, v115
	v_mul_f32_e32 v117, 0xbfb8aa3b, v117
	v_exp_f32_e32 v116, v116
	v_add_f32_e32 v118, 1.0, v118
	v_exp_f32_e32 v117, v117
	v_add_f32_e32 v119, 1.0, v119
	v_rcp_f32_e32 v118, v118
	v_add_f32_e32 v120, 1.0, v120
	v_rcp_f32_e32 v119, v119
	v_add_f32_e32 v121, 1.0, v121
	v_rcp_f32_e32 v120, v120
	v_add_f32_e32 v114, 1.0, v114
	v_rcp_f32_e32 v121, v121
	v_add_f32_e32 v115, 1.0, v115
	v_rcp_f32_e32 v114, v114
	v_add_f32_e32 v116, 1.0, v116
	v_rcp_f32_e32 v115, v115
	v_add_f32_e32 v117, 1.0, v117
	v_rcp_f32_e32 v116, v116
	v_rcp_f32_e32 v117, v117
	s_add_u32 s22, s34, 0x0
	s_addc_u32 s23, s35, 0
	v_cvt_pk_bf16_f32 v152, v118, v119
	v_cvt_pk_bf16_f32 v153, v120, v121
	v_cvt_pk_bf16_f32 v154, v114, v115
	v_cvt_pk_bf16_f32 v155, v116, v117
	global_store_dwordx4 v132, v[152:155], s[22:23] offset:256
	v_mul_f32_e32 v110, 0xbfb8aa3b, v110
	v_mul_f32_e32 v111, 0xbfb8aa3b, v111
	v_exp_f32_e32 v110, v110
	v_mul_f32_e32 v112, 0xbfb8aa3b, v112
	v_exp_f32_e32 v111, v111
	v_mul_f32_e32 v113, 0xbfb8aa3b, v113
	v_exp_f32_e32 v112, v112
	v_mul_f32_e32 v106, 0xbfb8aa3b, v106
	v_exp_f32_e32 v113, v113
	v_mul_f32_e32 v107, 0xbfb8aa3b, v107
	v_exp_f32_e32 v106, v106
	v_mul_f32_e32 v108, 0xbfb8aa3b, v108
	v_exp_f32_e32 v107, v107
	v_mul_f32_e32 v109, 0xbfb8aa3b, v109
	v_exp_f32_e32 v108, v108
	v_add_f32_e32 v110, 1.0, v110
	v_exp_f32_e32 v109, v109
	v_add_f32_e32 v111, 1.0, v111
	v_rcp_f32_e32 v110, v110
	v_add_f32_e32 v112, 1.0, v112
	v_rcp_f32_e32 v111, v111
	v_add_f32_e32 v113, 1.0, v113
	v_rcp_f32_e32 v112, v112
	v_add_f32_e32 v106, 1.0, v106
	v_rcp_f32_e32 v113, v113
	v_add_f32_e32 v107, 1.0, v107
	v_rcp_f32_e32 v106, v106
	v_add_f32_e32 v108, 1.0, v108
	v_rcp_f32_e32 v107, v107
	v_add_f32_e32 v109, 1.0, v109
	v_rcp_f32_e32 v108, v108
	v_rcp_f32_e32 v109, v109
	s_add_u32 s22, s34, 0x20000
	s_addc_u32 s23, s35, 0
	v_cvt_pk_bf16_f32 v148, v110, v111
	v_cvt_pk_bf16_f32 v149, v112, v113
	v_cvt_pk_bf16_f32 v150, v106, v107
	v_cvt_pk_bf16_f32 v151, v108, v109
	global_store_dwordx4 v132, v[148:151], s[22:23] offset:0
	v_mul_f32_e32 v102, 0xbfb8aa3b, v102
	v_mul_f32_e32 v103, 0xbfb8aa3b, v103
	v_exp_f32_e32 v102, v102
	v_mul_f32_e32 v104, 0xbfb8aa3b, v104
	v_exp_f32_e32 v103, v103
	v_mul_f32_e32 v105, 0xbfb8aa3b, v105
	v_exp_f32_e32 v104, v104
	v_mul_f32_e32 v98, 0xbfb8aa3b, v98
	v_exp_f32_e32 v105, v105
	v_mul_f32_e32 v99, 0xbfb8aa3b, v99
	v_exp_f32_e32 v98, v98
	v_mul_f32_e32 v100, 0xbfb8aa3b, v100
	v_exp_f32_e32 v99, v99
	v_mul_f32_e32 v101, 0xbfb8aa3b, v101
	v_exp_f32_e32 v100, v100
	v_add_f32_e32 v102, 1.0, v102
	v_exp_f32_e32 v101, v101
	v_add_f32_e32 v103, 1.0, v103
	v_rcp_f32_e32 v102, v102
	v_add_f32_e32 v104, 1.0, v104
	v_rcp_f32_e32 v103, v103
	v_add_f32_e32 v105, 1.0, v105
	v_rcp_f32_e32 v104, v104
	v_add_f32_e32 v98, 1.0, v98
	v_rcp_f32_e32 v105, v105
	v_add_f32_e32 v99, 1.0, v99
	v_rcp_f32_e32 v98, v98
	v_add_f32_e32 v100, 1.0, v100
	v_rcp_f32_e32 v99, v99
	v_add_f32_e32 v101, 1.0, v101
	v_rcp_f32_e32 v100, v100
	v_rcp_f32_e32 v101, v101
	s_add_u32 s22, s34, 0x20000
	s_addc_u32 s23, s35, 0
	v_cvt_pk_bf16_f32 v152, v102, v103
	v_cvt_pk_bf16_f32 v153, v104, v105
	v_cvt_pk_bf16_f32 v154, v98, v99
	v_cvt_pk_bf16_f32 v155, v100, v101
	global_store_dwordx4 v132, v[152:155], s[22:23] offset:256
	v_mul_f32_e32 v94, 0xbfb8aa3b, v94
	v_mul_f32_e32 v95, 0xbfb8aa3b, v95
	v_exp_f32_e32 v94, v94
	v_mul_f32_e32 v96, 0xbfb8aa3b, v96
	v_exp_f32_e32 v95, v95
	v_mul_f32_e32 v97, 0xbfb8aa3b, v97
; __device__ __forceinline__ u32x4 pack8(const f32x4 a, const f32x4 b) { u32x4 w; w.x = cvt_pk_bf16(a[0], a[1]); w.y = cvt_pk_bf16(a[2], a[3]); w.z = cvt_pk_bf16(b[0], b[1]); w.w = cvt_pk_bf16(b[2], b[3]); return w; }
; __device__ __forceinline__ float sigmoidf_(float x) { return __builtin_amdgcn_rcpf(1.0f + __builtin_amdgcn_exp2f(-1.4426950408889634f * x)); }
; template <int MODE>
; __device__ __forceinline__ void epi_body(const Epi& E0, const f32x4 (&acc)[2][2][4][2], const Unit& u, int wr, int wc, int fr, int fq) {
;     ...
;                     } else {
; #pragma unroll
;                         for (int j = 0; j < 4; ++j) { v0[j] = sigmoidf_(v0[j]); v1[j] = sigmoidf_(v1[j]); }
;                         *(u32x4*)(E.gates + (size_t)r * GATEW + (u.pn - 22) * 256 + cl) = pack8(v0, v1);
;                     }
	v_exp_f32_e32 v96, v96
	v_mul_f32_e32 v90, 0xbfb8aa3b, v90
	v_exp_f32_e32 v97, v97
	v_mul_f32_e32 v91, 0xbfb8aa3b, v91
	v_exp_f32_e32 v90, v90
	v_mul_f32_e32 v92, 0xbfb8aa3b, v92
	v_exp_f32_e32 v91, v91
	v_mul_f32_e32 v93, 0xbfb8aa3b, v93
	v_exp_f32_e32 v92, v92
	v_add_f32_e32 v94, 1.0, v94
	v_exp_f32_e32 v93, v93
	v_add_f32_e32 v95, 1.0, v95
	v_rcp_f32_e32 v94, v94
	v_add_f32_e32 v96, 1.0, v96
	v_rcp_f32_e32 v95, v95
	v_add_f32_e32 v97, 1.0, v97
	v_rcp_f32_e32 v96, v96
	v_add_f32_e32 v90, 1.0, v90
	v_rcp_f32_e32 v97, v97
	v_add_f32_e32 v91, 1.0, v91
	v_rcp_f32_e32 v90, v90
	v_add_f32_e32 v92, 1.0, v92
	v_rcp_f32_e32 v91, v91
	v_add_f32_e32 v93, 1.0, v93
	v_rcp_f32_e32 v92, v92
	v_rcp_f32_e32 v93, v93
	s_add_u32 s22, s34, 0x40000
	s_addc_u32 s23, s35, 0
	v_cvt_pk_bf16_f32 v148, v94, v95
	v_cvt_pk_bf16_f32 v149, v96, v97
	v_cvt_pk_bf16_f32 v150, v90, v91
	v_cvt_pk_bf16_f32 v151, v92, v93
	global_store_dwordx4 v132, v[148:151], s[22:23] offset:0
	v_mul_f32_e32 v86, 0xbfb8aa3b, v86
	v_mul_f32_e32 v87, 0xbfb8aa3b, v87
	v_exp_f32_e32 v86, v86
	v_mul_f32_e32 v88, 0xbfb8aa3b, v88
	v_exp_f32_e32 v87, v87
	v_mul_f32_e32 v89, 0xbfb8aa3b, v89
	v_exp_f32_e32 v88, v88
	v_mul_f32_e32 v82, 0xbfb8aa3b, v82
	v_exp_f32_e32 v89, v89
	v_mul_f32_e32 v83, 0xbfb8aa3b, v83
	v_exp_f32_e32 v82, v82
	v_mul_f32_e32 v84, 0xbfb8aa3b, v84
	v_exp_f32_e32 v83, v83
	v_mul_f32_e32 v85, 0xbfb8aa3b, v85
	v_exp_f32_e32 v84, v84
	v_add_f32_e32 v86, 1.0, v86
	v_exp_f32_e32 v85, v85
	v_add_f32_e32 v87, 1.0, v87
	v_rcp_f32_e32 v86, v86
	v_add_f32_e32 v88, 1.0, v88
	v_rcp_f32_e32 v87, v87
	v_add_f32_e32 v89, 1.0, v89
	v_rcp_f32_e32 v88, v88
	v_add_f32_e32 v82, 1.0, v82
	v_rcp_f32_e32 v89, v89
	v_add_f32_e32 v83, 1.0, v83
	v_rcp_f32_e32 v82, v82
	v_add_f32_e32 v84, 1.0, v84
	v_rcp_f32_e32 v83, v83
	v_add_f32_e32 v85, 1.0, v85
	v_rcp_f32_e32 v84, v84
	v_rcp_f32_e32 v85, v85
	s_add_u32 s22, s34, 0x40000
	s_addc_u32 s23, s35, 0
	v_cvt_pk_bf16_f32 v152, v86, v87
	v_cvt_pk_bf16_f32 v153, v88, v89
	v_cvt_pk_bf16_f32 v154, v82, v83
	v_cvt_pk_bf16_f32 v155, v84, v85
	global_store_dwordx4 v132, v[152:155], s[22:23] offset:256
	v_mul_f32_e32 v78, 0xbfb8aa3b, v78
	v_mul_f32_e32 v79, 0xbfb8aa3b, v79
	v_exp_f32_e32 v78, v78
	v_mul_f32_e32 v80, 0xbfb8aa3b, v80
	v_exp_f32_e32 v79, v79
	v_mul_f32_e32 v81, 0xbfb8aa3b, v81
	v_exp_f32_e32 v80, v80
	v_mul_f32_e32 v74, 0xbfb8aa3b, v74
	v_exp_f32_e32 v81, v81
	v_mul_f32_e32 v75, 0xbfb8aa3b, v75
	v_exp_f32_e32 v74, v74
	v_mul_f32_e32 v76, 0xbfb8aa3b, v76
	v_exp_f32_e32 v75, v75
	v_mul_f32_e32 v77, 0xbfb8aa3b, v77
	v_exp_f32_e32 v76, v76
	v_add_f32_e32 v78, 1.0, v78
	v_exp_f32_e32 v77, v77
	v_add_f32_e32 v79, 1.0, v79
	v_rcp_f32_e32 v78, v78
	v_add_f32_e32 v80, 1.0, v80
	v_rcp_f32_e32 v79, v79
	v_add_f32_e32 v81, 1.0, v81
	v_rcp_f32_e32 v80, v80
	v_add_f32_e32 v74, 1.0, v74
	v_rcp_f32_e32 v81, v81
	v_add_f32_e32 v75, 1.0, v75
	v_rcp_f32_e32 v74, v74
	v_add_f32_e32 v76, 1.0, v76
	v_rcp_f32_e32 v75, v75
	v_add_f32_e32 v77, 1.0, v77
	v_rcp_f32_e32 v76, v76
	v_rcp_f32_e32 v77, v77
	s_add_u32 s22, s34, 0x60000
	s_addc_u32 s23, s35, 0
	v_cvt_pk_bf16_f32 v148, v78, v79
	v_cvt_pk_bf16_f32 v149, v80, v81
	v_cvt_pk_bf16_f32 v150, v74, v75
	v_cvt_pk_bf16_f32 v151, v76, v77
	global_store_dwordx4 v132, v[148:151], s[22:23] offset:0
	v_mul_f32_e32 v70, 0xbfb8aa3b, v70
	v_mul_f32_e32 v71, 0xbfb8aa3b, v71
	v_exp_f32_e32 v70, v70
	v_mul_f32_e32 v72, 0xbfb8aa3b, v72
	v_exp_f32_e32 v71, v71
	v_mul_f32_e32 v73, 0xbfb8aa3b, v73
	v_exp_f32_e32 v72, v72
	v_mul_f32_e32 v66, 0xbfb8aa3b, v66
	v_exp_f32_e32 v73, v73
	v_mul_f32_e32 v67, 0xbfb8aa3b, v67
	v_exp_f32_e32 v66, v66
	v_mul_f32_e32 v68, 0xbfb8aa3b, v68
	v_exp_f32_e32 v67, v67
	v_mul_f32_e32 v69, 0xbfb8aa3b, v69
	v_exp_f32_e32 v68, v68
	v_add_f32_e32 v70, 1.0, v70
	v_exp_f32_e32 v69, v69
	v_add_f32_e32 v71, 1.0, v71
	v_rcp_f32_e32 v70, v70
	v_add_f32_e32 v72, 1.0, v72
	v_rcp_f32_e32 v71, v71
	v_add_f32_e32 v73, 1.0, v73
	v_rcp_f32_e32 v72, v72
	v_add_f32_e32 v66, 1.0, v66
	v_rcp_f32_e32 v73, v73
	v_add_f32_e32 v67, 1.0, v67
	v_rcp_f32_e32 v66, v66
	v_add_f32_e32 v68, 1.0, v68
	v_rcp_f32_e32 v67, v67
	v_add_f32_e32 v69, 1.0, v69
	v_rcp_f32_e32 v68, v68
	v_rcp_f32_e32 v69, v69
	s_add_u32 s22, s34, 0x60000
	s_addc_u32 s23, s35, 0
	v_cvt_pk_bf16_f32 v152, v70, v71
	v_cvt_pk_bf16_f32 v153, v72, v73
	v_cvt_pk_bf16_f32 v154, v66, v67
	v_cvt_pk_bf16_f32 v155, v68, v69
	global_store_dwordx4 v132, v[152:155], s[22:23] offset:256
	v_mul_f32_e32 v62, 0xbfb8aa3b, v62
	v_mul_f32_e32 v63, 0xbfb8aa3b, v63
	v_exp_f32_e32 v62, v62
	v_mul_f32_e32 v64, 0xbfb8aa3b, v64
	v_exp_f32_e32 v63, v63
	v_mul_f32_e32 v65, 0xbfb8aa3b, v65
	v_exp_f32_e32 v64, v64
	v_mul_f32_e32 v58, 0xbfb8aa3b, v58
	v_exp_f32_e32 v65, v65
	v_mul_f32_e32 v59, 0xbfb8aa3b, v59
	v_exp_f32_e32 v58, v58
	v_mul_f32_e32 v60, 0xbfb8aa3b, v60
	v_exp_f32_e32 v59, v59
	v_mul_f32_e32 v61, 0xbfb8aa3b, v61
	v_exp_f32_e32 v60, v60
	v_add_f32_e32 v62, 1.0, v62
	v_exp_f32_e32 v61, v61
	v_add_f32_e32 v63, 1.0, v63
	v_rcp_f32_e32 v62, v62
	v_add_f32_e32 v64, 1.0, v64
	v_rcp_f32_e32 v63, v63
	v_add_f32_e32 v65, 1.0, v65
	v_rcp_f32_e32 v64, v64
	v_add_f32_e32 v58, 1.0, v58
	v_rcp_f32_e32 v65, v65
	v_add_f32_e32 v59, 1.0, v59
	v_rcp_f32_e32 v58, v58
	v_add_f32_e32 v60, 1.0, v60
	v_rcp_f32_e32 v59, v59
	v_add_f32_e32 v61, 1.0, v61
	v_rcp_f32_e32 v60, v60
	v_rcp_f32_e32 v61, v61
	s_add_u32 s22, s34, 0x100000
	s_addc_u32 s23, s35, 0
	v_cvt_pk_bf16_f32 v148, v62, v63
	v_cvt_pk_bf16_f32 v149, v64, v65
	v_cvt_pk_bf16_f32 v150, v58, v59
	v_cvt_pk_bf16_f32 v151, v60, v61
	global_store_dwordx4 v132, v[148:151], s[22:23] offset:0
	v_mul_f32_e32 v54, 0xbfb8aa3b, v54
	v_mul_f32_e32 v55, 0xbfb8aa3b, v55
; __device__ __forceinline__ u32x4 pack8(const f32x4 a, const f32x4 b) { u32x4 w; w.x = cvt_pk_bf16(a[0], a[1]); w.y = cvt_pk_bf16(a[2], a[3]); w.z = cvt_pk_bf16(b[0], b[1]); w.w = cvt_pk_bf16(b[2], b[3]); return w; }
; __device__ __forceinline__ float sigmoidf_(float x) { return __builtin_amdgcn_rcpf(1.0f + __builtin_amdgcn_exp2f(-1.4426950408889634f * x)); }
; template <int MODE>
; __device__ __forceinline__ void epi_body(const Epi& E0, const f32x4 (&acc)[2][2][4][2], const Unit& u, int wr, int wc, int fr, int fq) {
;     ...
;                     } else {
; #pragma unroll
;                         for (int j = 0; j < 4; ++j) { v0[j] = sigmoidf_(v0[j]); v1[j] = sigmoidf_(v1[j]); }
;                         *(u32x4*)(E.gates + (size_t)r * GATEW + (u.pn - 22) * 256 + cl) = pack8(v0, v1);
;                     }
	v_exp_f32_e32 v54, v54
	v_mul_f32_e32 v56, 0xbfb8aa3b, v56
	v_exp_f32_e32 v55, v55
	v_mul_f32_e32 v57, 0xbfb8aa3b, v57
	v_exp_f32_e32 v56, v56
	v_mul_f32_e32 v50, 0xbfb8aa3b, v50
	v_exp_f32_e32 v57, v57
	v_mul_f32_e32 v51, 0xbfb8aa3b, v51
	v_exp_f32_e32 v50, v50
	v_mul_f32_e32 v52, 0xbfb8aa3b, v52
	v_exp_f32_e32 v51, v51
	v_mul_f32_e32 v53, 0xbfb8aa3b, v53
	v_exp_f32_e32 v52, v52
	v_add_f32_e32 v54, 1.0, v54
	v_exp_f32_e32 v53, v53
	v_add_f32_e32 v55, 1.0, v55
	v_rcp_f32_e32 v54, v54
	v_add_f32_e32 v56, 1.0, v56
	v_rcp_f32_e32 v55, v55
	v_add_f32_e32 v57, 1.0, v57
	v_rcp_f32_e32 v56, v56
	v_add_f32_e32 v50, 1.0, v50
	v_rcp_f32_e32 v57, v57
	v_add_f32_e32 v51, 1.0, v51
	v_rcp_f32_e32 v50, v50
	v_add_f32_e32 v52, 1.0, v52
	v_rcp_f32_e32 v51, v51
	v_add_f32_e32 v53, 1.0, v53
	v_rcp_f32_e32 v52, v52
	v_rcp_f32_e32 v53, v53
	s_add_u32 s22, s34, 0x100000
	s_addc_u32 s23, s35, 0
	v_cvt_pk_bf16_f32 v152, v54, v55
	v_cvt_pk_bf16_f32 v153, v56, v57
	v_cvt_pk_bf16_f32 v154, v50, v51
	v_cvt_pk_bf16_f32 v155, v52, v53
	global_store_dwordx4 v132, v[152:155], s[22:23] offset:256
	v_mul_f32_e32 v46, 0xbfb8aa3b, v46
	v_mul_f32_e32 v47, 0xbfb8aa3b, v47
	v_exp_f32_e32 v46, v46
	v_mul_f32_e32 v48, 0xbfb8aa3b, v48
	v_exp_f32_e32 v47, v47
	v_mul_f32_e32 v49, 0xbfb8aa3b, v49
	v_exp_f32_e32 v48, v48
	v_mul_f32_e32 v42, 0xbfb8aa3b, v42
	v_exp_f32_e32 v49, v49
	v_mul_f32_e32 v43, 0xbfb8aa3b, v43
	v_exp_f32_e32 v42, v42
	v_mul_f32_e32 v44, 0xbfb8aa3b, v44
	v_exp_f32_e32 v43, v43
	v_mul_f32_e32 v45, 0xbfb8aa3b, v45
	v_exp_f32_e32 v44, v44
	v_add_f32_e32 v46, 1.0, v46
	v_exp_f32_e32 v45, v45
	v_add_f32_e32 v47, 1.0, v47
	v_rcp_f32_e32 v46, v46
	v_add_f32_e32 v48, 1.0, v48
	v_rcp_f32_e32 v47, v47
	v_add_f32_e32 v49, 1.0, v49
	v_rcp_f32_e32 v48, v48
	v_add_f32_e32 v42, 1.0, v42
	v_rcp_f32_e32 v49, v49
	v_add_f32_e32 v43, 1.0, v43
	v_rcp_f32_e32 v42, v42
	v_add_f32_e32 v44, 1.0, v44
	v_rcp_f32_e32 v43, v43
	v_add_f32_e32 v45, 1.0, v45
	v_rcp_f32_e32 v44, v44
	v_rcp_f32_e32 v45, v45
	s_add_u32 s22, s34, 0x120000
	s_addc_u32 s23, s35, 0
	v_cvt_pk_bf16_f32 v148, v46, v47
	v_cvt_pk_bf16_f32 v149, v48, v49
	v_cvt_pk_bf16_f32 v150, v42, v43
	v_cvt_pk_bf16_f32 v151, v44, v45
	global_store_dwordx4 v132, v[148:151], s[22:23] offset:0
	v_mul_f32_e32 v38, 0xbfb8aa3b, v38
	v_mul_f32_e32 v39, 0xbfb8aa3b, v39
	v_exp_f32_e32 v38, v38
	v_mul_f32_e32 v40, 0xbfb8aa3b, v40
	v_exp_f32_e32 v39, v39
	v_mul_f32_e32 v41, 0xbfb8aa3b, v41
	v_exp_f32_e32 v40, v40
	v_mul_f32_e32 v34, 0xbfb8aa3b, v34
	v_exp_f32_e32 v41, v41
	v_mul_f32_e32 v35, 0xbfb8aa3b, v35
	v_exp_f32_e32 v34, v34
	v_mul_f32_e32 v36, 0xbfb8aa3b, v36
	v_exp_f32_e32 v35, v35
	v_mul_f32_e32 v37, 0xbfb8aa3b, v37
	v_exp_f32_e32 v36, v36
	v_add_f32_e32 v38, 1.0, v38
	v_exp_f32_e32 v37, v37
	v_add_f32_e32 v39, 1.0, v39
	v_rcp_f32_e32 v38, v38
	v_add_f32_e32 v40, 1.0, v40
	v_rcp_f32_e32 v39, v39
	v_add_f32_e32 v41, 1.0, v41
	v_rcp_f32_e32 v40, v40
	v_add_f32_e32 v34, 1.0, v34
	v_rcp_f32_e32 v41, v41
	v_add_f32_e32 v35, 1.0, v35
	v_rcp_f32_e32 v34, v34
	v_add_f32_e32 v36, 1.0, v36
	v_rcp_f32_e32 v35, v35
	v_add_f32_e32 v37, 1.0, v37
	v_rcp_f32_e32 v36, v36
	v_rcp_f32_e32 v37, v37
	s_add_u32 s22, s34, 0x120000
	s_addc_u32 s23, s35, 0
	v_cvt_pk_bf16_f32 v152, v38, v39
	v_cvt_pk_bf16_f32 v153, v40, v41
	v_cvt_pk_bf16_f32 v154, v34, v35
	v_cvt_pk_bf16_f32 v155, v36, v37
	global_store_dwordx4 v132, v[152:155], s[22:23] offset:256
	v_mul_f32_e32 v30, 0xbfb8aa3b, v30
	v_mul_f32_e32 v31, 0xbfb8aa3b, v31
	v_exp_f32_e32 v30, v30
	v_mul_f32_e32 v32, 0xbfb8aa3b, v32
	v_exp_f32_e32 v31, v31
	v_mul_f32_e32 v33, 0xbfb8aa3b, v33
	v_exp_f32_e32 v32, v32
	v_mul_f32_e32 v26, 0xbfb8aa3b, v26
	v_exp_f32_e32 v33, v33
	v_mul_f32_e32 v27, 0xbfb8aa3b, v27
	v_exp_f32_e32 v26, v26
	v_mul_f32_e32 v28, 0xbfb8aa3b, v28
	v_exp_f32_e32 v27, v27
	v_mul_f32_e32 v29, 0xbfb8aa3b, v29
	v_exp_f32_e32 v28, v28
	v_add_f32_e32 v30, 1.0, v30
	v_exp_f32_e32 v29, v29
	v_add_f32_e32 v31, 1.0, v31
	v_rcp_f32_e32 v30, v30
	v_add_f32_e32 v32, 1.0, v32
	v_rcp_f32_e32 v31, v31
	v_add_f32_e32 v33, 1.0, v33
	v_rcp_f32_e32 v32, v32
	v_add_f32_e32 v26, 1.0, v26
	v_rcp_f32_e32 v33, v33
	v_add_f32_e32 v27, 1.0, v27
	v_rcp_f32_e32 v26, v26
	v_add_f32_e32 v28, 1.0, v28
	v_rcp_f32_e32 v27, v27
	v_add_f32_e32 v29, 1.0, v29
	v_rcp_f32_e32 v28, v28
	v_rcp_f32_e32 v29, v29
	s_add_u32 s22, s34, 0x140000
	s_addc_u32 s23, s35, 0
	v_cvt_pk_bf16_f32 v148, v30, v31
	v_cvt_pk_bf16_f32 v149, v32, v33
	v_cvt_pk_bf16_f32 v150, v26, v27
	v_cvt_pk_bf16_f32 v151, v28, v29
	global_store_dwordx4 v132, v[148:151], s[22:23] offset:0
	v_mul_f32_e32 v22, 0xbfb8aa3b, v22
	v_mul_f32_e32 v23, 0xbfb8aa3b, v23
	v_exp_f32_e32 v22, v22
	v_mul_f32_e32 v24, 0xbfb8aa3b, v24
	v_exp_f32_e32 v23, v23
	v_mul_f32_e32 v25, 0xbfb8aa3b, v25
	v_exp_f32_e32 v24, v24
	v_mul_f32_e32 v18, 0xbfb8aa3b, v18
	v_exp_f32_e32 v25, v25
	v_mul_f32_e32 v19, 0xbfb8aa3b, v19
	v_exp_f32_e32 v18, v18
	v_mul_f32_e32 v20, 0xbfb8aa3b, v20
	v_exp_f32_e32 v19, v19
	v_mul_f32_e32 v21, 0xbfb8aa3b, v21
	v_exp_f32_e32 v20, v20
	v_add_f32_e32 v22, 1.0, v22
	v_exp_f32_e32 v21, v21
	v_add_f32_e32 v23, 1.0, v23
	v_rcp_f32_e32 v22, v22
	v_add_f32_e32 v24, 1.0, v24
	v_rcp_f32_e32 v23, v23
	v_add_f32_e32 v25, 1.0, v25
	v_rcp_f32_e32 v24, v24
	v_add_f32_e32 v18, 1.0, v18
; __device__ __forceinline__ u32x4 pack8(const f32x4 a, const f32x4 b) { u32x4 w; w.x = cvt_pk_bf16(a[0], a[1]); w.y = cvt_pk_bf16(a[2], a[3]); w.z = cvt_pk_bf16(b[0], b[1]); w.w = cvt_pk_bf16(b[2], b[3]); return w; }
; __device__ __forceinline__ float sigmoidf_(float x) { return __builtin_amdgcn_rcpf(1.0f + __builtin_amdgcn_exp2f(-1.4426950408889634f * x)); }
; template <int MODE>
; __device__ __forceinline__ void epi_body(const Epi& E0, const f32x4 (&acc)[2][2][4][2], const Unit& u, int wr, int wc, int fr, int fq) {
;     ...
;                 if constexpr (MODE == EM_INPROJ) {
;                     if (u.pn < 4) {
;                         const int col = u.pn * 256 + cl, g = col >> 4, cc = col & 15, chunk = r >> 4, t = r & 15;
;                         *(u32x4*)(E.assm + ((size_t)(g * NCHUNK + chunk) * 512 + t * 16 + cc)) = pack8(v0, v1);
;                     } else if (u.pn < 22) {
;                         const int hidx = (u.pn - 4) * 2 + bj, tensor = hidx / 12, head = hidx - tensor * 12, dcol = cl & 127, dsh = (head >> 2) * 2;
;                         int sbase, lsh; if (r < 32768) { sbase = r & ~8191; lsh = 13; } else { sbase = 32768; lsh = 14; }
;                         const int local = r - sbase, perm = sbase + ((local & ((1 << dsh) - 1)) << (lsh - dsh)) + (local >> dsh);
;                         *(u32x4*)(E.qkv + ((size_t)hidx * M_TOK + perm) * 128 + dcol) = pack8(v0, v1);
;                     } else {
; #pragma unroll
;                         for (int j = 0; j < 4; ++j) { v0[j] = sigmoidf_(v0[j]); v1[j] = sigmoidf_(v1[j]); }
;                         *(u32x4*)(E.gates + (size_t)r * GATEW + (u.pn - 22) * 256 + cl) = pack8(v0, v1);
;                     }
	v_rcp_f32_e32 v25, v25
	v_add_f32_e32 v19, 1.0, v19
	v_rcp_f32_e32 v18, v18
	v_add_f32_e32 v20, 1.0, v20
	v_rcp_f32_e32 v19, v19
	v_add_f32_e32 v21, 1.0, v21
	v_rcp_f32_e32 v20, v20
	v_rcp_f32_e32 v21, v21
	s_add_u32 s22, s34, 0x140000
	s_addc_u32 s23, s35, 0
	v_cvt_pk_bf16_f32 v152, v22, v23
	v_cvt_pk_bf16_f32 v153, v24, v25
	v_cvt_pk_bf16_f32 v154, v18, v19
	v_cvt_pk_bf16_f32 v155, v20, v21
	global_store_dwordx4 v132, v[152:155], s[22:23] offset:256
	v_mul_f32_e32 v14, 0xbfb8aa3b, v14
	v_mul_f32_e32 v15, 0xbfb8aa3b, v15
	v_exp_f32_e32 v14, v14
	v_mul_f32_e32 v16, 0xbfb8aa3b, v16
	v_exp_f32_e32 v15, v15
	v_mul_f32_e32 v17, 0xbfb8aa3b, v17
	v_exp_f32_e32 v16, v16
	v_mul_f32_e32 v10, 0xbfb8aa3b, v10
	v_exp_f32_e32 v17, v17
	v_mul_f32_e32 v11, 0xbfb8aa3b, v11
	v_exp_f32_e32 v10, v10
	v_mul_f32_e32 v12, 0xbfb8aa3b, v12
	v_exp_f32_e32 v11, v11
	v_mul_f32_e32 v13, 0xbfb8aa3b, v13
	v_exp_f32_e32 v12, v12
	v_add_f32_e32 v14, 1.0, v14
	v_exp_f32_e32 v13, v13
	v_add_f32_e32 v15, 1.0, v15
	v_rcp_f32_e32 v14, v14
	v_add_f32_e32 v16, 1.0, v16
	v_rcp_f32_e32 v15, v15
	v_add_f32_e32 v17, 1.0, v17
	v_rcp_f32_e32 v16, v16
	v_add_f32_e32 v10, 1.0, v10
	v_rcp_f32_e32 v17, v17
	v_add_f32_e32 v11, 1.0, v11
	v_rcp_f32_e32 v10, v10
	v_add_f32_e32 v12, 1.0, v12
	v_rcp_f32_e32 v11, v11
	v_add_f32_e32 v13, 1.0, v13
	v_rcp_f32_e32 v12, v12
	v_rcp_f32_e32 v13, v13
	s_add_u32 s22, s34, 0x160000
	s_addc_u32 s23, s35, 0
	v_cvt_pk_bf16_f32 v148, v14, v15
	v_cvt_pk_bf16_f32 v149, v16, v17
	v_cvt_pk_bf16_f32 v150, v10, v11
	v_cvt_pk_bf16_f32 v151, v12, v13
	global_store_dwordx4 v132, v[148:151], s[22:23] offset:0
	v_mul_f32_e32 v6, 0xbfb8aa3b, v6
	v_mul_f32_e32 v7, 0xbfb8aa3b, v7
	v_exp_f32_e32 v6, v6
	v_mul_f32_e32 v8, 0xbfb8aa3b, v8
	v_exp_f32_e32 v7, v7
	v_mul_f32_e32 v9, 0xbfb8aa3b, v9
	v_exp_f32_e32 v8, v8
	v_mul_f32_e32 v2, 0xbfb8aa3b, v2
	v_exp_f32_e32 v9, v9
	v_mul_f32_e32 v3, 0xbfb8aa3b, v3
	v_exp_f32_e32 v2, v2
	v_mul_f32_e32 v4, 0xbfb8aa3b, v4
	v_exp_f32_e32 v3, v3
	v_mul_f32_e32 v5, 0xbfb8aa3b, v5
	v_exp_f32_e32 v4, v4
	v_add_f32_e32 v6, 1.0, v6
	v_exp_f32_e32 v5, v5
	v_add_f32_e32 v7, 1.0, v7
	v_rcp_f32_e32 v6, v6
	v_add_f32_e32 v8, 1.0, v8
	v_rcp_f32_e32 v7, v7
	v_add_f32_e32 v9, 1.0, v9
	v_rcp_f32_e32 v8, v8
	v_add_f32_e32 v2, 1.0, v2
	v_rcp_f32_e32 v9, v9
	v_add_f32_e32 v3, 1.0, v3
	v_rcp_f32_e32 v2, v2
	v_add_f32_e32 v4, 1.0, v4
	v_rcp_f32_e32 v3, v3
	v_add_f32_e32 v5, 1.0, v5
	v_rcp_f32_e32 v4, v4
	v_rcp_f32_e32 v5, v5
	s_add_u32 s22, s34, 0x160000
	s_addc_u32 s23, s35, 0
	v_cvt_pk_bf16_f32 v152, v6, v7
	v_cvt_pk_bf16_f32 v153, v8, v9
	v_cvt_pk_bf16_f32 v154, v2, v3
	v_cvt_pk_bf16_f32 v155, v4, v5
	global_store_dwordx4 v132, v[152:155], s[22:23] offset:256
	s_mov_b64 s[8:9], 0
	s_branch .LBB0_374
.Lepi_inproj_orig:
	v_mov_b32_e32 v146, v158
	v_mov_b32_e32 v152, v159
	s_mov_b64 s[8:9], 0
	v_readlane_b32 s22, v251, 63
	v_readlane_b32 s23, v250, 0
	s_add_u32 s8, s22, s8
	s_mov_b64 s[26:27], 0
	s_addc_u32 s9, s23, s9
	s_add_u32 s26, s8, 0x27000000
	v_readlane_b32 s22, v250, 22
	s_addc_u32 s27, s9, 0
	s_lshl_b32 s21, s21, 8
	v_lshl_add_u32 v132, v146, 3, s22
	v_readlane_b32 s22, v250, 21
	s_add_i32 s21, s21, s22
	v_and_b32_e32 v0, 0x78, v132
	v_add_u32_e32 v148, s21, v152
	v_lshlrev_b32_e32 v0, 1, v0
	v_lshl_add_u64 v[130:131], s[8:9], 0, v[0:1]
	v_ashrrev_i32_e32 v149, 31, v148
	v_min_i32_e32 v0, 0x8000, v148
	s_cmp_gt_i32 s28, 3
	s_mov_b64 s[22:23], 0xc000000
	v_lshlrev_b64 v[150:151], 13, v[148:149]
	v_and_b32_e32 v153, 0xffffe000, v0
	v_cmp_gt_i32_e32 vcc, s25, v148
	s_cselect_b64 s[34:35], -1, 0
	v_lshl_add_u64 v[130:131], v[130:131], 0, s[22:23]
	v_lshl_add_u64 v[150:151], s[26:27], 0, v[150:151]
	v_cndmask_b32_e64 v155, 14, 13, vcc
	v_sub_u32_e32 v154, v148, v153
	s_mov_b64 s[92:93], -1
	s_and_b64 vcc, exec, s[34:35]
	s_cbranch_vccz .LBB0_252
	s_cmp_lt_u32 s28, 22
	s_cbranch_scc1 .LBB0_249
	v_mul_f32_e32 v162, 0xbfb8aa3b, v129
	v_mul_f32_e32 v133, 0xbfb8aa3b, v122
	v_mul_f32_e32 v149, 0xbfb8aa3b, v123
	v_mul_f32_e32 v156, 0xbfb8aa3b, v128
	v_mul_f32_e32 v157, 0xbfb8aa3b, v124
	v_exp_f32_e32 v162, v162
	v_mul_f32_e32 v163, 0xbfb8aa3b, v125
	v_mul_f32_e32 v0, 0xbfb8aa3b, v126
	v_exp_f32_e32 v133, v133
	v_mul_f32_e32 v147, 0xbfb8aa3b, v127
	v_exp_f32_e32 v149, v149
	v_exp_f32_e32 v156, v156
	v_exp_f32_e32 v157, v157
	v_exp_f32_e32 v163, v163
	v_exp_f32_e32 v0, v0
	v_exp_f32_e32 v147, v147
	v_add_f32_e32 v162, 1.0, v162
	v_add_f32_e32 v133, 1.0, v133
	v_add_f32_e32 v149, 1.0, v149
	v_add_f32_e32 v156, 1.0, v156
	v_add_f32_e32 v157, 1.0, v157
	v_rcp_f32_e32 v164, v162
	v_add_f32_e32 v162, 1.0, v163
	v_add_f32_e32 v0, 1.0, v0
	v_rcp_f32_e32 v133, v133
	v_add_f32_e32 v147, 1.0, v147
	v_rcp_f32_e32 v149, v149
	v_rcp_f32_e32 v156, v156
	v_rcp_f32_e32 v157, v157
	v_rcp_f32_e32 v165, v162
	v_rcp_f32_e32 v0, v0
	v_rcp_f32_e32 v147, v147
	s_lshl_b32 s21, s28, 8
	s_add_i32 s92, s21, 0xffffea00
	s_ashr_i32 s93, s92, 31
	v_cvt_pk_bf16_f32 v163, v156, v164
	v_cvt_pk_bf16_f32 v164, v133, v149
	v_cvt_pk_bf16_f32 v165, v157, v165
	v_lshl_add_u64 v[156:157], s[92:93], 1, v[150:151]
	v_ashrrev_i32_e32 v133, 31, v132
	v_cvt_pk_bf16_f32 v162, v0, v147
	v_lshl_add_u64 v[156:157], v[132:133], 1, v[156:157]
	s_mov_b64 s[92:93], 0
	global_store_dwordx4 v[156:157], v[162:165], off

; template <bool COOP>
; __global__ void __launch_bounds__(512, 2) fwd_kernel(Params p) {
;     ...
;     }
; }
.LBB0_641:
	s_nop 0
	s_nop 0
	s_nop 0
	s_nop 0
	s_nop 0
	s_nop 0
	s_nop 0
	s_nop 0
	s_nop 0
	s_nop 0
	s_nop 0
	s_nop 0
	s_nop 0
	s_nop 0
	s_nop 0
	s_nop 0
	s_nop 0
	s_nop 0
	s_nop 0
	s_nop 0
	s_nop 0
	s_nop 0
	s_nop 0
	s_nop 0
	s_nop 0
	s_nop 0
	s_nop 0
	s_nop 0
	s_nop 0
	s_nop 0
	s_nop 0
	s_nop 0
	s_nop 0
	s_nop 0
	s_nop 0
	s_nop 0
	s_nop 0
	s_nop 0
	s_nop 0
	s_nop 0
	s_endpgm
